# grid barrier: L1 invalidate issued by wave 1 on arrival (overlaps the arrive/poll of thread 0) instead of after the poll
# speedup vs baseline: 1.0338x; 1.0338x over previous
.Lxb1_done:
	s_waitcnt vmcnt(0)
	s_mov_b32 s98, s10
.LBB0_271:
	v_writelane_b32 v241, s45, 13
	s_or_b64 exec, exec, s[0:1]
	v_readlane_b32 s24, v242, 1
	v_readlane_b32 s26, v242, 3
	v_readlane_b32 s27, v242, 4
	s_add_u32 s42, s26, 0x30f8100
	v_mov_b32_e32 v1, v137
	v_readlane_b32 s0, v242, 0
	s_addc_u32 s43, s27, 0
	s_waitcnt lgkmcnt(0)
	v_readfirstlane_b32 s99, v137
	s_cmp_lg_u32 s99, 64
	s_cbranch_scc1 .Lxbi1_skip
	buffer_inv sc1
	s_waitcnt vmcnt(0)
.Lxbi1_skip:
	s_barrier
	s_ashr_i32 s2, s50, 3
	s_and_b32 s1, s0, 7
	s_mul_i32 s1, s1, s2
	s_ashr_i32 s0, s0, 3
	s_add_i32 s60, s1, s0
	v_writelane_b32 v241, s2, 14
	s_ashr_i32 s2, s60, 2
	v_writelane_b32 v241, s2, 15
	s_lshl_b32 s62, s60, 5
	s_lshl_b32 s2, s60, 6
	s_and_b32 s45, s62, 64
	s_and_b32 s2, s2, 64
	s_cmpk_lt_i32 s60, 0xbe4
	s_cselect_b64 s[4:5], -1, 0
	v_writelane_b32 v241, s4, 16
	s_mov_b32 s94, s2
	s_lshl_b32 s2, s2, 2
	v_readlane_b32 s25, v242, 2
	v_writelane_b32 v241, s5, 17
	s_add_u32 s2, s24, s2
	v_writelane_b32 v241, s2, 18
	s_addc_u32 s2, s25, 0
	s_add_u32 s20, s26, 0x5678100
	s_addc_u32 s21, s27, 0
	s_add_u32 s88, s26, 0x44f8100
	s_addc_u32 s89, s27, 0
	v_readlane_b32 s4, v242, 26
	v_writelane_b32 v241, s2, 20
	v_readlane_b32 s5, v242, 27
	s_add_u32 s2, s4, 0x30000
	v_writelane_b32 v241, s2, 21
	s_addc_u32 s2, s5, 0
	v_writelane_b32 v241, s2, 22
	s_add_u32 s2, s26, 0x2f78000
	v_readlane_b32 s18, v242, 40
	v_writelane_b32 v241, s2, 23
	s_addc_u32 s2, s27, 0
	v_readlane_b32 s19, v242, 41
	s_add_u32 s83, s18, 0xb00000
	s_addc_u32 s56, s19, 0
	v_writelane_b32 v241, s2, 24
	s_add_u32 s2, s26, 0x2980000
	v_readlane_b32 s16, v242, 38
	s_addc_u32 s3, s27, 0
	v_readlane_b32 s17, v242, 39
	s_add_u32 s57, s16, 0x1600000
	v_writelane_b32 v241, s2, 25
	s_addc_u32 s86, s17, 0
	v_and_b32_e32 v0, 63, v1
	v_ashrrev_i32_e32 v2, 6, v1
	v_bfe_u32 v4, v1, 3, 3
	v_readlane_b32 s6, v242, 28
	v_readlane_b32 s7, v242, 29
	v_readlane_b32 s8, v242, 30
	v_readlane_b32 s9, v242, 31
	v_readlane_b32 s10, v242, 32
	v_readlane_b32 s11, v242, 33
	v_readlane_b32 s12, v242, 34
	v_readlane_b32 s13, v242, 35
	v_readlane_b32 s14, v242, 36
	v_readlane_b32 s15, v242, 37
	v_writelane_b32 v241, s3, 26
	s_add_u32 s2, s26, 0x1900000
	v_and_b32_e32 v5, 1, v2
	v_bfe_u32 v8, v1, 4, 2
	v_lshl_or_b32 v93, v2, 5, v4
	v_lshrrev_b32_e32 v4, 1, v1
	v_lshlrev_b32_e32 v2, 12, v2
	v_lshlrev_b32_e32 v7, 4, v0
	s_addc_u32 s3, s27, 0
	v_readlane_b32 s4, v242, 10
	v_and_b32_e32 v92, 15, v1
	v_bfe_u32 v6, v1, 1, 3
	v_add3_u32 v114, 0, v2, v7
	v_bitop3_b32 v2, v8, v4, 7 bitop3:0x78
	v_mov_b32_e32 v95, 0
	v_lshlrev_b32_e32 v94, 8, v5
	v_readlane_b32 s5, v242, 11
	s_add_u32 s87, s4, 0x400000
	v_lshlrev_b32_e32 v115, 4, v2
	v_bitop3_b32 v2, v8, v6, 4 bitop3:0x36
	v_lshl_add_u64 v[6:7], s[24:25], 0, v[94:95]
	v_lshlrev_b32_e32 v94, 2, v92
	s_addc_u32 s54, s5, 0
	v_lshl_add_u64 v[96:97], v[6:7], 0, v[94:95]
	s_add_u32 s92, s26, 0xc00000
	v_lshlrev_b32_e32 v94, 3, v8
	v_lshlrev_b32_e32 v116, 4, v2
	v_and_b32_e32 v2, 7, v1
	v_bitop3_b32 v9, v8, v1, 7 bitop3:0x78
	s_addc_u32 s93, s27, 0
	v_writelane_b32 v241, s20, 27
	s_lshl_b32 s4, s1, 6
	s_lshl_b32 s48, s0, 6
	v_lshl_add_u64 v[98:99], s[20:21], 0, v[94:95]
	v_lshlrev_b32_e32 v94, 1, v92
	s_lshl_b32 s1, s1, 2
	s_lshl_b32 s0, s0, 2
	v_bitop3_b32 v10, v8, v2, 4 bitop3:0x36
	v_lshl_add_u64 v[100:101], s[88:89], 0, v[94:95]
	s_add_i32 s0, s1, s0
	v_lshlrev_b32_e32 v94, 4, v9
	s_add_i32 s25, s50, 0xfffff9c0
	s_mov_b64 s[66:67], s[70:71]
	s_mov_b64 s[68:69], s[72:73]
	v_readlane_b32 s19, v242, 25
	v_writelane_b32 v241, s21, 28
	v_lshl_add_u64 v[102:103], s[26:27], 0, v[94:95]
	v_lshlrev_b32_e32 v94, 4, v10
	s_add_i32 s61, s0, 0x3c300
	s_lshl_b32 s63, s25, 2
	s_mov_b64 s[70:71], s[74:75]
	s_mov_b64 s[72:73], s[76:77]
	s_mov_b64 s[74:75], s[78:79]
	s_add_i32 s19, s60, 0xdb28
	s_lshl_b32 s24, s60, 7
	v_lshl_add_u64 v[104:105], s[26:27], 0, v[94:95]
	s_add_i32 s27, s60, 0xede8
	v_writelane_b32 v241, s60, 29
	v_lshrrev_b32_e32 v4, 4, v1
	v_ashrrev_i32_e32 v3, 7, v1
	v_writelane_b32 v241, s61, 30
	v_writelane_b32 v241, s62, 31
	v_writelane_b32 v241, s63, 32
	v_writelane_b32 v241, s64, 33
	v_writelane_b32 v241, s65, 34
	v_writelane_b32 v241, s66, 35
	v_writelane_b32 v241, s67, 36
	v_writelane_b32 v241, s68, 37
	v_writelane_b32 v241, s69, 38
	v_writelane_b32 v241, s70, 39
	v_writelane_b32 v241, s71, 40
	v_xor_b32_e32 v2, v8, v1
	v_bitop3_b32 v1, v4, v1, 4 bitop3:0x36
	v_writelane_b32 v241, s72, 41
	v_lshlrev_b32_e32 v1, 3, v1
	v_writelane_b32 v241, s73, 42
	v_lshlrev_b32_e32 v117, 6, v3
	v_lshlrev_b32_e32 v2, 3, v2
	v_and_b32_e32 v4, 56, v1
	v_lshlrev_b32_e32 v120, 13, v3
	v_lshlrev_b32_e32 v122, 13, v5
	v_add_u32_e32 v1, 0, v115
	v_add_u32_e32 v3, 0, v116
	v_readlane_b32 s17, v242, 23
	v_writelane_b32 v241, s74, 43
	v_or_b32_e32 v0, 48, v0
	v_and_b32_e32 v2, 56, v2
	v_lshlrev_b32_e32 v121, 7, v92
	v_add_u32_e32 v11, v1, v120
	v_add_u32_e32 v1, v1, v122
	v_add_u32_e32 v12, v3, v120
	v_add_u32_e32 v3, v3, v122
	v_readlane_b32 s6, v242, 12
	v_readlane_b32 s7, v242, 13
	v_readlane_b32 s9, v242, 15
	v_readlane_b32 s10, v242, 16
	v_readlane_b32 s11, v242, 17
	v_readlane_b32 s12, v242, 18
	v_readlane_b32 s13, v242, 19
	v_readlane_b32 s14, v242, 20
	v_readlane_b32 s15, v242, 21
	v_readlane_b32 s16, v242, 22
	v_readlane_b32 s18, v242, 24
	s_add_i32 s17, s50, 0xffffe700
	v_writelane_b32 v241, s75, 44
	s_mov_b64 s[68:69], s[2:3]
	v_lshlrev_b32_e32 v118, 6, v5
	v_lshlrev_b32_e32 v119, 2, v8
	v_lshl_or_b32 v123, v8, 7, v92
	s_mov_b32 s95, s4
	s_add_i32 s49, s4, s48
	s_lshl_b32 s16, s50, 8
	s_lshl_b32 s18, s17, 6
	s_add_i32 s21, s0, 0x37800
	s_lshl_b32 s22, s50, 4
	s_lshl_b32 s23, s17, 2
	s_lshl_b32 s91, s50, 6
	s_lshl_b32 s46, s50, 5
	s_lshl_b32 s47, s50, 7
	s_lshl_b32 s26, s25, 6
	v_mov_b32_e32 v124, 0x358637bd
	v_lshlrev_b32_e32 v106, 1, v2
	v_lshlrev_b32_e32 v108, 1, v4
	v_add_u32_e32 v125, v11, v121
	v_add_u32_e32 v126, v1, v121
	v_add_u32_e32 v127, v12, v121
	v_add_u32_e32 v128, v3, v121
	v_lshlrev_b32_e32 v110, 2, v0
	v_mov_b32_e32 v129, 0xc0
	v_mov_b32_e32 v130, 0x3800000
	v_mov_b32_e32 v131, 0x2800000
	v_bfrev_b32_e32 v132, 32
	v_mov_b32_e32 v133, 0x3000000
	s_mov_b32 s90, s0
	s_movk_i32 s7, 0x1600
	s_mov_b32 s84, 0x5b76000
	s_movk_i32 s80, 0x600
	s_movk_i32 s81, 0x104
	s_movk_i32 s82, 0x5800
	s_movk_i32 s6, 0xaff
	s_movk_i32 s85, 0xffc0
	s_movk_i32 s55, 0x2800
	s_mov_b32 s58, 0
	s_mov_b32 s59, 0
	s_mov_b32 s20, 0
	s_mov_b32 s28, 0
	s_mov_b32 s29, 0
	s_mov_b32 s9, 0
	s_mov_b64 s[10:11], 0x4000
	s_mov_b64 s[12:13], 0x80
	s_mov_b64 s[14:15], 0x4080
	s_mov_b64 s[30:31], 0xc000
	v_writelane_b32 v241, s68, 45
	v_readlane_b32 s8, v242, 14
	s_nop 0
	v_writelane_b32 v241, s69, 46
	s_branch .LBB0_273

.LBB0_834:
	s_or_b64 exec, exec, s[0:1]
	v_readlane_b32 s0, v242, 1
	v_readlane_b32 s2, v242, 3
	v_readlane_b32 s3, v242, 4
	s_add_u32 s52, s2, 0x5b78100
	s_addc_u32 s53, s3, 0
	s_add_u32 s54, s2, 0x9278100
	s_addc_u32 s55, s3, 0
	s_add_u32 s62, s2, 0xb078100
	s_addc_u32 s63, s3, 0
	s_add_u32 s64, s2, 0xbf78100
	s_addc_u32 s65, s3, 0
	s_add_u32 s74, s2, 0xce78100
	s_addc_u32 s75, s3, 0
	s_add_u32 s56, s2, 0xd5f8100
	s_addc_u32 s57, s3, 0
	s_add_u32 s60, s2, 0xdd78100
	s_addc_u32 s61, s3, 0
	s_add_u32 s44, s2, 0xecc8100
	s_waitcnt lgkmcnt(0)
	v_mov_b32_e32 v0, v137
	s_addc_u32 s45, s3, 0
	v_readlane_b32 s4, v242, 0
	v_readfirstlane_b32 s99, v137
	s_cmp_lg_u32 s99, 64
	s_cbranch_scc1 .Lxbi2_skip
	buffer_inv sc1
	s_waitcnt vmcnt(0)
.Lxbi2_skip:
	s_barrier
	s_cmpk_gt_i32 s4, 0x1df
	v_readlane_b32 s1, v242, 2
	s_cbranch_scc1 .LBB0_853
	v_lshlrev_b32_e32 v9, 4, v0
	s_movk_i32 s0, 0x70
	v_bitop3_b32 v11, v9, s0, v0 bitop3:0x48
	v_readlane_b32 s0, v242, 46
	v_mov_b32_e32 v37, 0
	v_and_b32_e32 v10, 0xffffff80, v9
	v_and_b32_e32 v36, 0xf0, v9
	v_readlane_b32 s1, v242, 47
	v_ashrrev_i32_e32 v9, 1, v0
	v_and_b32_e32 v123, 0xffffffe0, v9
	v_lshl_add_u64 v[38:39], s[0:1], 0, v[36:37]
	v_add_u32_e32 v16, 0x100, v0
	v_add_u32_e32 v19, 0x200, v0
	v_add_u32_e32 v22, 0x300, v0
	v_lshrrev_b32_e32 v9, 5, v9
	s_mov_b32 s0, 0xb000
	v_bfe_u32 v8, v0, 4, 2
	v_lshlrev_b32_e32 v4, 3, v0
	v_ashrrev_i32_e32 v13, 4, v0
	v_ashrrev_i32_e32 v16, 4, v16
	v_ashrrev_i32_e32 v19, 4, v19
	v_ashrrev_i32_e32 v22, 4, v22
	v_mul_lo_u32 v29, v9, s0
	s_movk_i32 s0, 0x1600
	v_and_b32_e32 v122, 15, v0
	v_bfe_u32 v1, v0, 1, 3
	v_lshrrev_b32_e32 v5, 4, v0
	v_and_b32_e32 v2, 0xffffffc0, v4
	v_xor_b32_e32 v15, v13, v0
	v_xor_b32_e32 v18, v16, v0
	v_xor_b32_e32 v21, v19, v0
	v_xor_b32_e32 v0, v22, v0
	v_mad_u32_u24 v124, v8, s0, v29
	s_movk_i32 s0, 0x3000
	v_add_u32_e32 v6, 0x800, v2
	v_lshl_add_u32 v12, v122, 8, 0
	v_lshlrev_b32_e32 v15, 4, v15
	v_lshlrev_b32_e32 v18, 4, v18
	v_lshlrev_b32_e32 v21, 4, v21
	v_lshlrev_b32_e32 v0, 4, v0
	v_bitop3_b32 v24, v5, v1, 3 bitop3:0x6c
	v_lshlrev_b32_e32 v25, 7, v122
	v_bitop3_b32 v1, v8, v1, 4 bitop3:0x36
	v_bitop3_b32 v5, v5, v122, 3 bitop3:0x6c
	v_bitop3_b32 v26, v8, v122, 4 bitop3:0x36
	v_bitop3_b32 v27, v8, v122, 8 bitop3:0x36
	v_bitop3_b32 v28, v8, v122, 12 bitop3:0x36
	v_mul_lo_u32 v29, v9, s0
	s_movk_i32 s0, 0x600
	v_ashrrev_i32_e32 v3, 31, v2
	v_and_b32_e32 v4, 56, v4
	v_ashrrev_i32_e32 v7, 31, v6
	v_add_u32_e32 v10, 0, v10
	v_lshl_add_u32 v14, v13, 8, 0
	v_and_b32_e32 v15, 0xf0, v15
	v_lshl_add_u32 v17, v16, 8, 0
	v_and_b32_e32 v18, 0xf0, v18
	v_lshl_add_u32 v20, v19, 8, 0
	v_and_b32_e32 v21, 0xf0, v21
	v_lshl_add_u32 v23, v22, 8, 0
	v_and_b32_e32 v0, 0xf0, v0
	v_lshlrev_b32_e32 v24, 4, v24
	v_sub_u32_e32 v25, v12, v25
	v_lshlrev_b32_e32 v1, 4, v1
	v_lshlrev_b32_e32 v5, 4, v5
	v_lshlrev_b32_e32 v26, 4, v26
	v_lshlrev_b32_e32 v27, 4, v27
	v_lshlrev_b32_e32 v28, 4, v28
	v_lshlrev_b32_e32 v36, 4, v8
	v_mad_u32_u24 v126, v8, s0, v29
	v_lshlrev_b32_e32 v8, 5, v8
	s_mov_b32 s1, 0
	v_cmp_eq_u32_e32 vcc, 0, v122
	v_lshl_add_u64 v[40:41], s[44:45], 0, v[36:37]
	s_lshl_b32 s5, s4, 12
	s_lshl_b32 s6, s50, 12
	v_lshl_or_b32 v125, s4, 6, v122
	v_lshlrev_b32_e32 v127, 7, v22
	s_lshl_b32 s7, s4, 13
	s_lshl_b32 s8, s50, 13
	v_lshlrev_b32_e32 v128, 7, v19
	v_lshlrev_b32_e32 v129, 7, v16
	v_lshlrev_b32_e32 v130, 7, v13
	v_lshl_or_b32 v131, v9, 8, v8
	v_lshlrev_b64 v[42:43], 1, v[2:3]
	v_lshlrev_b32_e32 v44, 1, v4
	v_mov_b32_e32 v45, v37
	v_lshlrev_b64 v[46:47], 1, v[6:7]
	v_add_u32_e32 v132, v10, v11
	v_add_u32_e32 v133, v14, v15
	v_add_u32_e32 v134, v17, v18
	v_add_u32_e32 v135, v20, v21
	v_add_u32_e32 v136, v23, v0
	v_add_u32_e32 v138, v25, v24
	v_add_u32_e32 v139, v25, v1
	v_add_u32_e32 v140, v12, v5
	v_add_u32_e32 v141, v12, v26
	v_add_u32_e32 v142, v12, v27
	v_add_u32_e32 v143, v12, v28
	v_mov_b32_e32 v144, 0x1000
	s_branch .LBB0_837

.LBB0_905:
	v_writelane_b32 v241, s44, 47
	s_nop 1
	v_writelane_b32 v241, s45, 48
	s_or_b64 exec, exec, s[0:1]
	v_readlane_b32 s0, v242, 1
	v_readlane_b32 s2, v242, 3
	v_readlane_b32 s3, v242, 4
	s_add_u32 s76, s2, 0x30f4000
	s_addc_u32 s77, s3, 0
	s_add_u32 s4, s2, 0x2ff4000
	v_writelane_b32 v241, s4, 49
	s_addc_u32 s4, s3, 0
	v_writelane_b32 v241, s4, 50
	s_add_u32 s4, s2, 0x3034000
	v_writelane_b32 v241, s4, 51
	s_addc_u32 s4, s3, 0
	v_writelane_b32 v241, s4, 52
	s_add_u32 s4, s2, 0x3074000
	v_writelane_b32 v241, s4, 21
	s_addc_u32 s4, s3, 0
	v_writelane_b32 v241, s4, 22
	s_add_u32 s4, s2, 0x30b4000
	v_writelane_b32 v241, s4, 23
	s_addc_u32 s4, s3, 0
	s_add_u32 s70, s2, 0xddc8100
	s_addc_u32 s71, s3, 0
	v_readlane_b32 s1, v242, 2
	s_add_u32 s33, s0, 0x4800000
	v_writelane_b32 v241, s4, 24
	s_addc_u32 s67, s1, 0
	v_readlane_b32 s0, v242, 60
	v_readlane_b32 s4, v241, 0
	v_readlane_b32 s5, v241, 1
	v_readlane_b32 s6, v241, 2
	v_readlane_b32 s7, v241, 3
	v_readlane_b32 s8, v241, 4
	v_readlane_b32 s9, v241, 5
	v_readlane_b32 s10, v241, 6
	v_readlane_b32 s11, v241, 7
	v_readlane_b32 s12, v241, 8
	v_readlane_b32 s13, v241, 9
	v_readlane_b32 s14, v241, 10
	v_readlane_b32 s15, v241, 11
	v_writelane_b32 v241, s88, 16
	v_mbcnt_lo_u32_b32 v136, -1, 0
	s_cmp_lg_u64 s[12:13], 0
	v_writelane_b32 v241, s89, 17
	v_mbcnt_hi_u32_b32 v139, -1, v136
	v_writelane_b32 v241, s33, 15
	s_cselect_b64 s[72:73], -1, 0
	s_add_i32 s58, 0, 0x12000
	s_waitcnt lgkmcnt(0)
	v_and_b32_e32 v0, 64, v139
	v_writelane_b32 v241, s67, 20
	v_mov_b32_e32 v144, -1
	s_mov_b32 s45, 0
	v_mov_b32_e32 v89, 0
	s_mov_b32 s59, 0x1c000
	s_movk_i32 s40, 0xfefe
	s_movk_i32 s41, 0x180
	s_movk_i32 s48, 0x580
	s_movk_i32 s49, 0x600
	s_add_i32 s69, 0, 0x6000
	s_add_i32 s96, 0, 0x500
	s_add_i32 s97, 0, 0x6500
	v_mov_b32_e32 v138, s58
	v_xor_b32_e32 v140, 16, v139
	v_add_u32_e32 v141, 64, v0
	v_xor_b32_e32 v142, 32, v139
	v_mov_b32_e32 v143, 0xf149f2ca
	v_writelane_b32 v241, s72, 18
	v_readfirstlane_b32 s99, v137
	s_cmp_lg_u32 s99, 64
	s_cbranch_scc1 .Lxbi3_skip
	buffer_inv sc1
	s_waitcnt vmcnt(0)
.Lxbi3_skip:
	s_barrier
	v_readlane_b32 s1, v242, 61
	v_readlane_b32 s2, v242, 62
	v_readlane_b32 s3, v242, 63
	v_writelane_b32 v241, s73, 19
	s_branch .LBB0_909

.LBB0_1030:
	s_or_b64 exec, exec, s[0:1]
	s_waitcnt lgkmcnt(0)
	v_mov_b32_e32 v0, v137
	v_readlane_b32 s0, v242, 0
	v_readfirstlane_b32 s99, v137
	s_cmp_lg_u32 s99, 64
	s_cbranch_scc1 .Lxbi4_skip
	buffer_inv sc1
	s_waitcnt vmcnt(0)
.Lxbi4_skip:
	s_barrier
	s_nop 0
	v_ashrrev_i32_e32 v1, 6, v0
	s_waitcnt vmcnt(7)
	v_lshl_add_u32 v4, s0, 2, v1
	s_movk_i32 s0, 0x2800
	v_cmp_gt_i32_e32 vcc, s0, v4
	s_and_saveexec_b64 s[0:1], vcc
	s_cbranch_execz .LBB0_1033
	s_waitcnt vmcnt(0) lgkmcnt(0)
	v_readfirstlane_b32 s2, v4
	v_readlane_b32 s4, v242, 42
	v_readlane_b32 s5, v242, 43
	v_readlane_b32 s6, v242, 3
	v_readlane_b32 s7, v242, 4
	s_load_dword s3, s[4:5], 0x0
	s_sub_u32 s20, s4, 0x118
	s_subb_u32 s21, s5, 0
	s_load_dwordx2 s[22:23], s[20:21], 0xe0
	s_load_dwordx2 s[24:25], s[20:21], 0xe8
	v_and_b32_e32 v11, 63, v137
	v_lshrrev_b32_e32 v9, 4, v11
	v_and_b32_e32 v11, 15, v11
	v_lshlrev_b32_e32 v11, 2, v11
	v_lshl_add_u32 v5, v9, 6, v11
	v_and_b32_e32 v10, 1, v9
	v_add_u32_e32 v10, 4, v10
	v_lshl_add_u32 v7, v10, 6, v11
	v_lshlrev_b32_e32 v6, 2, v5
	v_lshlrev_b32_e32 v8, 2, v7
	v_lshlrev_b32_e32 v5, 1, v5
	v_lshlrev_b32_e32 v7, 1, v7
	v_lshlrev_b32_e32 v9, 2, v9
	v_lshlrev_b32_e32 v10, 2, v10
	v_mov_b32_e32 v126, 0x3a27c5ac
	v_mov_b32_e32 v127, 0x3c800000
	s_add_u32 s8, s6, 0xddc8100
	s_addc_u32 s9, s7, 0
	s_add_u32 s10, s6, 0xe548100
	s_addc_u32 s11, s7, 0
	s_add_u32 s12, s6, 0xd5f8100
	s_addc_u32 s13, s7, 0
	s_add_u32 s14, s6, 0x5b78d00
	s_addc_u32 s15, s7, 0
	s_add_u32 s16, s6, 0xdd78100
	s_addc_u32 s17, s7, 0
	s_add_u32 s18, s6, 0x30f8600
	s_addc_u32 s19, s7, 0
	s_waitcnt lgkmcnt(0)
	s_lshl_b32 s3, s3, 2
	global_load_dwordx4 v[12:15], v6, s[22:23]
	global_load_dwordx4 v[16:19], v8, s[22:23]
	global_load_dwordx4 v[20:23], v6, s[24:25]
	global_load_dwordx4 v[24:27], v8, s[24:25]
	s_mul_i32 s4, s2, 0x300
	s_add_u32 s20, s8, s4
	s_addc_u32 s21, s9, 0
	s_add_u32 s22, s10, s4
	s_addc_u32 s23, s11, 0
	s_add_u32 s24, s12, s4
	s_addc_u32 s25, s13, 0
	s_mul_i32 s4, s2, 0x1600
	s_add_u32 s26, s14, s4
	s_addc_u32 s27, s15, 0
	s_lshl_b32 s4, s2, 5
	s_add_u32 s28, s16, s4
	s_addc_u32 s29, s17, 0
	global_load_dwordx2 v[28:29], v5, s[20:21]
	global_load_dwordx2 v[30:31], v5, s[22:23]
	global_load_dwordx2 v[32:33], v5, s[24:25]
	global_load_dwordx4 v[34:37], v6, s[26:27]
	global_load_dword v38, v9, s[28:29]
	global_load_dwordx2 v[40:41], v7, s[20:21]
	global_load_dwordx2 v[42:43], v7, s[22:23]
	global_load_dwordx2 v[44:45], v7, s[24:25]
	global_load_dwordx4 v[46:49], v8, s[26:27]
	global_load_dword v50, v10, s[28:29]
	s_waitcnt vmcnt(0)

.LBB0_1085:
	s_or_b64 exec, exec, s[0:1]
	v_mov_b32_e32 v3, v137
	s_waitcnt lgkmcnt(0)
	v_readfirstlane_b32 s99, v137
	s_cmp_lg_u32 s99, 64
	s_cbranch_scc1 .Lxbi5_skip
	buffer_inv sc1
	s_waitcnt vmcnt(0)
.Lxbi5_skip:
	s_barrier
	v_readlane_b32 s0, v242, 0
	v_and_b32_e32 v0, 63, v3
	s_waitcnt vmcnt(3)
	v_ashrrev_i32_e32 v10, 6, v3
	v_bfe_u32 v18, v3, 4, 2
	v_lshrrev_b32_e32 v2, 1, v3
	v_bfe_u32 v4, v3, 1, 3
	v_lshlrev_b32_e32 v138, 4, v0
	v_bitop3_b32 v0, v18, v2, 7 bitop3:0x78
	v_add_u32_e32 v6, 4, v10
	v_bfe_u32 v134, v3, 3, 3
	v_lshlrev_b32_e32 v141, 4, v0
	v_bitop3_b32 v0, v18, v4, 4 bitop3:0x36
	v_lshlrev_b32_e32 v4, 3, v6
	v_or_b32_e32 v5, v4, v134
	s_waitcnt vmcnt(2)
	v_lshrrev_b32_e32 v20, 1, v5
	v_ashrrev_i32_e32 v5, 31, v4
	v_lshlrev_b64 v[86:87], 10, v[4:5]
	v_add_u32_e32 v5, 8, v10
	s_and_b32 s1, s0, 7
	v_xor_b32_e32 v7, v20, v3
	v_lshlrev_b32_e32 v145, 10, v6
	v_lshlrev_b32_e32 v6, 3, v5
	s_mul_i32 s4, s1, s41
	s_ashr_i32 s0, s0, 3
	v_lshlrev_b32_e32 v4, 3, v7
	v_or_b32_e32 v7, v6, v134
	v_ashrrev_i32_e32 v1, 7, v3
	v_and_b32_e32 v13, 1, v10
	s_add_i32 s4, s4, s0
	s_movk_i32 s0, 0x50
	v_lshrrev_b32_e32 v21, 1, v7
	v_and_b32_e32 v15, 15, v3
	v_lshlrev_b32_e32 v142, 4, v0
	v_mul_lo_u32 v0, v1, s0
	v_lshlrev_b32_e32 v80, 7, v13
	v_mov_b32_e32 v81, 0
	v_xor_b32_e32 v8, v21, v3
	v_ashrrev_i32_e32 v7, 31, v6
	v_lshlrev_b32_e32 v146, 10, v5
	v_add_u32_e32 v5, 12, v10
	v_or_b32_e32 v16, v0, v15
	v_lshl_or_b32 v143, v18, 2, v0
	v_lshl_add_u64 v[0:1], s[54:55], 0, v[80:81]
	v_lshlrev_b32_e32 v80, 1, v15
	v_lshlrev_b64 v[88:89], 10, v[6:7]
	v_lshlrev_b32_e32 v6, 3, v8
	v_lshlrev_b32_e32 v8, 3, v5
	v_lshlrev_b32_e32 v147, 10, v5
	v_add_u32_e32 v5, 16, v10
	v_lshl_or_b32 v135, v10, 5, v134
	v_lshlrev_b32_e32 v140, 12, v10
	v_lshl_add_u64 v[82:83], v[0:1], 0, v[80:81]
	v_lshlrev_b32_e32 v0, 3, v10
	v_lshlrev_b32_e32 v144, 10, v10
	v_or_b32_e32 v7, v8, v134
	v_ashrrev_i32_e32 v9, 31, v8
	v_lshlrev_b32_e32 v10, 3, v5
	v_lshrrev_b32_e32 v7, 1, v7
	v_lshlrev_b64 v[90:91], 10, v[8:9]
	v_or_b32_e32 v9, v10, v134
	v_xor_b32_e32 v11, v7, v3
	v_lshrrev_b32_e32 v9, 1, v9
	v_lshlrev_b32_e32 v148, 10, v5
	v_xor_b32_e32 v5, v18, v3
	v_lshlrev_b32_e32 v8, 3, v11
	v_xor_b32_e32 v12, v9, v3
	v_ashrrev_i32_e32 v11, 31, v10
	v_lshlrev_b32_e32 v5, 3, v5
	v_lshlrev_b64 v[92:93], 10, v[10:11]
	v_lshlrev_b32_e32 v10, 3, v12
	v_and_b32_e32 v12, 56, v5
	v_lshrrev_b32_e32 v5, 4, v3
	v_or_b32_e32 v1, v0, v134
	v_or_b32_e32 v11, 4, v5
	v_bitop3_b32 v5, v5, v3, 4 bitop3:0x36
	v_lshrrev_b32_e32 v17, 1, v1
	v_ashrrev_i32_e32 v1, 31, v0
	v_lshlrev_b32_e32 v5, 3, v5
	v_lshlrev_b64 v[84:85], 10, v[0:1]
	v_and_b32_e32 v14, 56, v5
	v_lshlrev_b64 v[0:1], 11, v[0:1]
	v_bitop3_b32 v5, v17, 7, v3 bitop3:0x48
	v_readlane_b32 s0, v242, 1
	v_xor_b32_e32 v2, v17, v3
	v_lshlrev_b32_e32 v149, 7, v16
	v_lshl_or_b32 v16, v5, 4, v0
	v_mov_b32_e32 v17, v1
	v_readlane_b32 s1, v242, 2
	v_readlane_b32 s2, v242, 3
	v_readlane_b32 s3, v242, 4
	s_mov_b64 s[0:1], 0x30f8180
	v_bitop3_b32 v5, v20, 7, v3 bitop3:0x48
	v_lshl_add_u64 v[16:17], s[2:3], 0, v[16:17]
	v_lshl_add_u64 v[94:95], v[16:17], 0, s[0:1]
	v_lshl_or_b32 v16, v5, 4, v0
	v_mov_b32_e32 v17, v1
	v_lshl_add_u64 v[16:17], s[2:3], 0, v[16:17]
	s_mov_b64 s[0:1], 0x3108180
	v_bitop3_b32 v5, v21, 7, v3 bitop3:0x48
	v_lshl_add_u64 v[96:97], v[16:17], 0, s[0:1]
	v_lshl_or_b32 v16, v5, 4, v0
	v_mov_b32_e32 v17, v1
	v_lshl_add_u64 v[16:17], s[2:3], 0, v[16:17]
	s_mov_b64 s[0:1], 0x3118180
	v_bitop3_b32 v5, v7, 7, v3 bitop3:0x48
	v_lshl_add_u64 v[98:99], v[16:17], 0, s[0:1]
	v_lshl_or_b32 v16, v5, 4, v0
	v_mov_b32_e32 v17, v1
	v_bitop3_b32 v5, v9, 7, v3 bitop3:0x48
	v_lshl_add_u64 v[16:17], s[2:3], 0, v[16:17]
	s_mov_b64 s[0:1], 0x3128180
	v_lshl_or_b32 v0, v5, 4, v0
	v_lshl_add_u64 v[100:101], v[16:17], 0, s[0:1]
	v_lshl_add_u64 v[0:1], s[2:3], 0, v[0:1]
	s_mov_b64 s[0:1], 0x3138180
	v_lshl_add_u64 v[102:103], v[0:1], 0, s[0:1]
	v_bitop3_b32 v0, v18, 7, v3 bitop3:0x48
	v_lshlrev_b32_e32 v2, 3, v2
	v_lshlrev_b32_e32 v80, 4, v0
	v_bitop3_b32 v0, v11, 7, v3 bitop3:0x48
	v_add_u32_e32 v19, 0, v140
	v_and_b32_e32 v2, 56, v2
	v_and_b32_e32 v4, 56, v4
	v_and_b32_e32 v6, 56, v6
	v_and_b32_e32 v8, 56, v8
	v_and_b32_e32 v10, 56, v10
	v_lshl_add_u64 v[104:105], s[2:3], 0, v[80:81]
	v_lshlrev_b32_e32 v80, 4, v0
	s_mov_b32 s5, 0
	v_add_u32_e32 v139, 0, v138
	v_lshlrev_b32_e32 v150, 13, v13
	v_lshlrev_b32_e32 v151, 7, v15
	v_lshl_add_u64 v[106:107], s[2:3], 0, v[80:81]
	v_lshlrev_b32_e32 v80, 1, v2
	v_lshlrev_b32_e32 v108, 1, v4
	v_lshlrev_b32_e32 v110, 1, v6
	v_lshlrev_b32_e32 v112, 1, v8
	v_lshlrev_b32_e32 v114, 1, v10
	v_lshlrev_b32_e32 v116, 1, v12
	v_add_u32_e32 v152, v19, v138
	v_lshlrev_b32_e32 v118, 1, v14
	s_waitcnt vmcnt(0)
	s_branch .LBB0_1087

.Lxbi6_skip:
	s_barrier
	s_nop 0
	v_ashrrev_i32_e32 v1, 6, v0
	v_lshl_add_u32 v1, s0, 2, v1
	v_readlane_b32 s0, v241, 12
	s_nop 1
	v_mul_lo_u32 v28, v1, s0
	v_add_u32_e32 v1, s0, v28
	v_min_i32_e32 v31, 0x2800, v1
	v_cmp_lt_i32_e32 vcc, v28, v31
	s_and_saveexec_b64 s[0:1], vcc
	s_xor_b64 s[2:3], exec, s[0:1]
	s_cbranch_execz .LBB0_1149
	v_readfirstlane_b32 s6, v28
	v_readfirstlane_b32 s7, v31
	v_readlane_b32 s36, v242, 42
	v_readlane_b32 s37, v242, 43
	v_readlane_b32 s14, v242, 1
	v_readlane_b32 s15, v242, 2
	v_readlane_b32 s20, v242, 3
	v_readlane_b32 s21, v242, 4
	v_and_b32_e32 v236, 63, v137
	v_lshlrev_b32_e32 v237, 3, v236
	v_lshlrev_b32_e32 v236, 4, v236
	v_mov_b32_e32 v238, 0x358637bd
	s_sub_u32 s36, s36, 0x118
	s_subb_u32 s37, s37, 0
	s_load_dwordx2 s[10:11], s[36:37], 0x60
	s_load_dwordx2 s[12:13], s[36:37], 0x68
	s_load_dwordx4 s[16:19], s[36:37], 0x0
	s_add_u32 s22, s20, 0x2f90000
	s_addc_u32 s23, s21, 0
	s_mov_b32 s8, -1
	s_waitcnt lgkmcnt(0)
	s_cmp_lt_u32 s6, 0x2000
	s_cselect_b32 s24, s16, s18
	s_cselect_b32 s25, s17, s19
	s_cselect_b32 s9, 0, 0x2000
	s_sub_u32 s9, s6, s9
	s_lshl_b32 s9, s9, 12
	s_add_u32 s24, s24, s9
	s_addc_u32 s25, s25, 0
	s_lshl_b32 s9, s6, 11
	s_add_u32 s9, s9, 0x9278100
	s_add_u32 s26, s20, s9
	s_addc_u32 s27, s21, 0
	global_load_dwordx2 v[204:205], v237, s[26:27] offset:0
	global_load_dwordx2 v[206:207], v237, s[26:27] offset:512
	global_load_dwordx2 v[208:209], v237, s[26:27] offset:1024
	global_load_dwordx2 v[210:211], v237, s[26:27] offset:1536
	global_load_dwordx4 v[188:191], v236, s[24:25] offset:0
	global_load_dwordx4 v[192:195], v236, s[24:25] offset:1024
	global_load_dwordx4 v[196:199], v236, s[24:25] offset:2048
	global_load_dwordx4 v[200:203], v236, s[24:25] offset:3072

.LBB0_1201:
	s_or_b64 exec, exec, s[0:1]
	v_mov_b32_e32 v1, v137
	s_waitcnt lgkmcnt(0)
	v_readfirstlane_b32 s99, v137
	s_cmp_lg_u32 s99, 64
	s_cbranch_scc1 .Lxbi7_skip
	buffer_inv sc1
	s_waitcnt vmcnt(0)
.Lxbi7_skip:
	s_barrier
	v_readlane_b32 s0, v242, 0
	v_and_b32_e32 v0, 63, v1
	v_ashrrev_i32_e32 v2, 6, v1
	v_bfe_u32 v7, v1, 3, 3
	v_and_b32_e32 v4, 1, v2
	v_bfe_u32 v6, v1, 4, 2
	v_lshl_or_b32 v82, v2, 5, v7
	v_lshrrev_b32_e32 v7, 1, v1
	v_lshlrev_b32_e32 v2, 12, v2
	v_lshlrev_b32_e32 v0, 4, v0
	v_bfe_u32 v8, v1, 1, 3
	v_add3_u32 v83, 0, v2, v0
	v_bitop3_b32 v0, v6, v7, 7 bitop3:0x78
	v_lshlrev_b32_e32 v84, 4, v0
	v_bitop3_b32 v0, v6, v8, 4 bitop3:0x36
	v_lshlrev_b32_e32 v85, 4, v0
	v_and_b32_e32 v0, 7, v1
	v_bitop3_b32 v8, v6, v0, 4 bitop3:0x36
	v_lshrrev_b32_e32 v0, 2, v1
	v_ashrrev_i32_e32 v3, 7, v1
	s_and_b32 s1, s0, 7
	v_lshrrev_b32_e32 v2, 4, v1
	v_and_b32_e32 v0, 12, v0
	v_and_b32_e32 v5, 15, v1
	s_mul_i32 s8, s1, s41
	s_ashr_i32 s0, s0, 3
	v_bitop3_b32 v7, v6, v1, 7 bitop3:0x78
	v_lshl_or_b32 v87, v3, 6, v0
	v_xor_b32_e32 v0, v6, v1
	v_bitop3_b32 v1, v2, v1, 4 bitop3:0x36
	s_add_i32 s8, s8, s0
	v_mov_b32_e32 v65, 0
	v_lshlrev_b32_e32 v1, 3, v1
	v_lshlrev_b32_e32 v64, 1, v5
	v_readlane_b32 s0, v242, 1
	v_lshlrev_b32_e32 v0, 3, v0
	v_and_b32_e32 v2, 56, v1
	v_lshlrev_b32_e32 v88, 13, v3
	v_lshlrev_b32_e32 v90, 13, v4
	v_add_u32_e32 v1, 0, v84
	v_add_u32_e32 v3, 0, v85
	v_lshl_add_u64 v[66:67], s[52:53], 0, v[64:65]
	v_lshlrev_b32_e32 v64, 4, v7
	v_readlane_b32 s2, v242, 3
	v_readlane_b32 s3, v242, 4
	v_lshlrev_b32_e32 v86, 6, v4
	v_and_b32_e32 v0, 56, v0
	v_lshlrev_b32_e32 v89, 7, v5
	v_add_u32_e32 v4, v1, v88
	v_add_u32_e32 v1, v1, v90
	v_add_u32_e32 v6, v3, v88
	v_add_u32_e32 v3, v3, v90
	v_readlane_b32 s1, v242, 2
	v_lshl_add_u64 v[68:69], s[2:3], 0, v[64:65]
	v_lshlrev_b32_e32 v64, 4, v8
	s_mov_b32 s9, 0
	s_lshl_b32 s10, s8, 5
	s_lshl_b32 s11, s8, 7
	v_lshl_add_u64 v[70:71], s[2:3], 0, v[64:65]
	v_lshlrev_b32_e32 v64, 1, v0
	v_add_u32_e32 v91, 0x4000, v83
	v_lshlrev_b32_e32 v72, 1, v2
	s_mov_b64 s[0:1], 0x4000
	v_add_u32_e32 v92, 0x400, v83
	v_add_u32_e32 v93, 0x4400, v83
	s_mov_b64 s[2:3], 0x8000
	v_add_u32_e32 v94, 0x800, v83
	v_add_u32_e32 v95, 0x4800, v83
	s_mov_b64 s[4:5], 0xc000
	v_add_u32_e32 v96, 0xc00, v83
	v_add_u32_e32 v97, 0x4c00, v83
	s_movk_i32 s12, 0x1600
	v_add_u32_e32 v98, v4, v89
	v_add_u32_e32 v99, v1, v89
	v_add_u32_e32 v100, v6, v89
	v_add_u32_e32 v101, v3, v89
	s_branch .LBB0_1203

.Lxbi8_skip:
	s_barrier
	v_readlane_b32 s0, v242, 0
	v_and_b32_e32 v0, 63, v3
	v_bfe_u32 v11, v3, 4, 2
	v_lshrrev_b32_e32 v2, 1, v3
	v_ashrrev_i32_e32 v5, 6, v3
	v_bfe_u32 v4, v3, 1, 3
	v_lshlrev_b32_e32 v138, 4, v0
	v_bitop3_b32 v0, v11, v2, 7 bitop3:0x78
	v_lshlrev_b32_e32 v141, 4, v0
	v_bitop3_b32 v0, v11, v4, 4 bitop3:0x36
	v_add_u32_e32 v4, 4, v5
	v_bfe_u32 v134, v3, 3, 3
	v_lshlrev_b32_e32 v2, 3, v4
	s_and_b32 s1, s0, 7
	v_or_b32_e32 v6, v2, v134
	s_mul_i32 s4, s1, s41
	s_ashr_i32 s0, s0, 3
	v_lshrrev_b32_e32 v18, 1, v6
	v_ashrrev_i32_e32 v1, 7, v3
	s_add_i32 s4, s4, s0
	s_movk_i32 s0, 0x50
	s_movk_i32 s2, 0xb00
	v_xor_b32_e32 v6, v18, v3
	v_lshlrev_b32_e32 v142, 4, v0
	v_mul_lo_u32 v0, v1, s0
	v_mad_i64_i32 v[86:87], s[0:1], v2, s2, 0
	v_lshlrev_b32_e32 v2, 3, v6
	v_add_u32_e32 v6, 8, v5
	v_lshlrev_b32_e32 v145, 10, v4
	v_lshlrev_b32_e32 v4, 3, v6
	v_and_b32_e32 v7, 1, v5
	v_or_b32_e32 v8, v4, v134
	v_and_b32_e32 v9, 15, v3
	v_lshlrev_b32_e32 v80, 7, v7
	v_mov_b32_e32 v81, 0
	v_lshrrev_b32_e32 v19, 1, v8
	v_or_b32_e32 v14, v0, v9
	v_lshl_or_b32 v143, v11, 2, v0
	v_lshl_add_u64 v[0:1], s[54:55], 0, v[80:81]
	v_lshlrev_b32_e32 v80, 1, v9
	v_xor_b32_e32 v8, v19, v3
	v_lshl_or_b32 v135, v5, 5, v134
	v_lshlrev_b32_e32 v140, 12, v5
	v_lshl_add_u64 v[82:83], v[0:1], 0, v[80:81]
	v_lshlrev_b32_e32 v1, 3, v5
	v_lshlrev_b32_e32 v144, 10, v5
	v_mad_i64_i32 v[88:89], s[0:1], v4, s2, 0
	v_lshlrev_b32_e32 v4, 3, v8
	v_add_u32_e32 v8, 12, v5
	v_add_u32_e32 v5, 16, v5
	v_or_b32_e32 v0, v1, v134
	v_lshlrev_b32_e32 v146, 10, v6
	v_lshlrev_b32_e32 v6, 3, v8
	v_lshlrev_b32_e32 v147, 10, v8
	v_lshlrev_b32_e32 v8, 3, v5
	s_movk_i32 s6, 0x1600
	v_lshrrev_b32_e32 v16, 1, v0
	v_mad_i64_i32 v[84:85], s[0:1], v1, s2, 0
	v_mad_i64_i32 v[90:91], s[0:1], v6, s2, 0
	v_mad_i64_i32 v[92:93], s[0:1], v8, s2, 0
	v_lshlrev_b32_e32 v149, 7, v14
	v_mad_i64_i32 v[14:15], s[0:1], v1, s6, 0
	v_bitop3_b32 v1, v16, 7, v3 bitop3:0x48
	v_readlane_b32 s0, v242, 1
	v_xor_b32_e32 v0, v16, v3
	v_or_b32_e32 v10, v6, v134
	v_lshl_or_b32 v16, v1, 4, v14
	v_mov_b32_e32 v17, v15
	v_readlane_b32 s1, v242, 2
	v_readlane_b32 s2, v242, 3
	v_readlane_b32 s3, v242, 4
	v_lshrrev_b32_e32 v20, 1, v10
	s_mov_b64 s[0:1], 0x5b78180
	v_lshl_add_u64 v[16:17], s[2:3], 0, v[16:17]
	v_bitop3_b32 v1, v18, 7, v3 bitop3:0x48
	v_xor_b32_e32 v10, v20, v3
	v_lshl_add_u64 v[94:95], v[16:17], 0, s[0:1]
	v_lshl_or_b32 v16, v1, 4, v14
	v_mov_b32_e32 v17, v15
	v_lshlrev_b32_e32 v6, 3, v10
	v_or_b32_e32 v10, v8, v134
	v_lshl_add_u64 v[16:17], s[2:3], 0, v[16:17]
	s_mov_b64 s[0:1], 0x5ba4180
	v_bitop3_b32 v1, v19, 7, v3 bitop3:0x48
	v_lshrrev_b32_e32 v21, 1, v10
	v_lshlrev_b32_e32 v148, 10, v5
	v_xor_b32_e32 v5, v11, v3
	v_lshl_add_u64 v[96:97], v[16:17], 0, s[0:1]
	v_lshl_or_b32 v16, v1, 4, v14
	v_mov_b32_e32 v17, v15
	v_xor_b32_e32 v10, v21, v3
	v_lshlrev_b32_e32 v5, 3, v5
	v_lshl_add_u64 v[16:17], s[2:3], 0, v[16:17]
	s_mov_b64 s[0:1], 0x5bd0180
	v_bitop3_b32 v1, v20, 7, v3 bitop3:0x48
	v_lshlrev_b32_e32 v8, 3, v10
	v_and_b32_e32 v10, 56, v5
	v_lshrrev_b32_e32 v5, 4, v3
	v_lshl_add_u64 v[98:99], v[16:17], 0, s[0:1]
	v_lshl_or_b32 v16, v1, 4, v14
	v_bitop3_b32 v1, v21, 7, v3 bitop3:0x48
	v_or_b32_e32 v22, 4, v5
	v_bitop3_b32 v5, v5, v3, 4 bitop3:0x36
	v_mov_b32_e32 v17, v15
	v_lshl_or_b32 v14, v1, 4, v14
	v_bitop3_b32 v1, v11, 7, v3 bitop3:0x48
	v_lshlrev_b32_e32 v0, 3, v0
	v_lshlrev_b32_e32 v5, 3, v5
	v_lshl_add_u64 v[16:17], s[2:3], 0, v[16:17]
	s_mov_b64 s[0:1], 0x5bfc180
	v_lshlrev_b32_e32 v80, 4, v1
	v_bitop3_b32 v1, v22, 7, v3 bitop3:0x48
	v_add_u32_e32 v13, 0, v140
	v_and_b32_e32 v0, 56, v0
	v_and_b32_e32 v2, 56, v2
	v_and_b32_e32 v4, 56, v4
	v_and_b32_e32 v6, 56, v6
	v_and_b32_e32 v8, 56, v8
	v_and_b32_e32 v12, 56, v5
	v_lshl_add_u64 v[100:101], v[16:17], 0, s[0:1]
	v_lshl_add_u64 v[14:15], s[2:3], 0, v[14:15]
	s_mov_b64 s[0:1], 0x5c28180
	v_lshl_add_u64 v[104:105], s[2:3], 0, v[80:81]
	v_lshlrev_b32_e32 v80, 4, v1
	s_mov_b32 s5, 0
	v_add_u32_e32 v139, 0, v138
	v_lshlrev_b32_e32 v150, 13, v7
	v_lshlrev_b32_e32 v151, 7, v9
	v_lshl_add_u64 v[102:103], v[14:15], 0, s[0:1]
	v_lshl_add_u64 v[106:107], s[2:3], 0, v[80:81]
	v_lshlrev_b32_e32 v80, 1, v0
	v_lshlrev_b32_e32 v108, 1, v2
	v_lshlrev_b32_e32 v110, 1, v4
	v_lshlrev_b32_e32 v112, 1, v6
	v_lshlrev_b32_e32 v114, 1, v8
	v_lshlrev_b32_e32 v116, 1, v10
	v_add_u32_e32 v152, v13, v138
	v_lshlrev_b32_e32 v118, 1, v12
	s_branch .LBB0_1261

.LBB0_1317:
	s_or_b64 exec, exec, s[0:1]
	s_lshl_b32 s68, s66, 2
	s_abs_i32 s0, s68
	v_cvt_f32_u32_e32 v1, s0
	s_sub_i32 s3, 0, s0
	s_add_i32 s1, s68, 0x27ff
	s_xor_b32 s2, s1, s68
	v_rcp_iflag_f32_e32 v1, v1
	s_abs_i32 s1, s1
	s_ashr_i32 s2, s2, 31
	s_waitcnt lgkmcnt(0)
	v_mov_b32_e32 v0, v137
	v_mul_f32_e32 v1, 0x4f7ffffe, v1
	v_cvt_u32_f32_e32 v1, v1
	v_readfirstlane_b32 s99, v137
	s_cmp_lg_u32 s99, 64
	s_cbranch_scc1 .Lxbi9_skip
	buffer_inv sc1
	s_waitcnt vmcnt(0)
.Lxbi9_skip:
	s_barrier
	v_readfirstlane_b32 s4, v1
	s_mul_i32 s3, s3, s4
	s_mul_hi_u32 s3, s4, s3
	s_add_i32 s4, s4, s3
	s_mul_hi_u32 s3, s1, s4
	s_mul_i32 s4, s3, s0
	s_sub_i32 s1, s1, s4
	s_add_i32 s4, s3, 1
	s_sub_i32 s5, s1, s0
	s_cmp_ge_u32 s1, s0
	s_cselect_b32 s3, s4, s3
	s_cselect_b32 s1, s5, s1
	s_add_i32 s4, s3, 1
	s_cmp_ge_u32 s1, s0
	s_cselect_b32 s0, s4, s3
	s_xor_b32 s0, s0, s2
	s_sub_i32 s1, s0, s2
	v_ashrrev_i32_e32 v2, 6, v0
	v_readlane_b32 s0, v242, 0
	v_writelane_b32 v242, s1, 56
	s_nop 0
	v_lshl_add_u32 v1, s0, 2, v2
	v_mul_lo_u32 v28, v1, s1
	v_add_u32_e32 v1, s1, v28
	v_min_i32_e32 v90, 0x2800, v1
	v_cmp_lt_i32_e32 vcc, v28, v90
	s_and_saveexec_b64 s[0:1], vcc
	s_cbranch_execz .LBB0_1322
	v_readfirstlane_b32 s6, v28
	v_readfirstlane_b32 s7, v90
	v_readlane_b32 s36, v242, 42
	v_readlane_b32 s37, v242, 43
	v_readlane_b32 s14, v242, 1
	v_readlane_b32 s15, v242, 2
	v_readlane_b32 s20, v242, 3
	v_readlane_b32 s21, v242, 4
	v_and_b32_e32 v236, 63, v137
	v_lshlrev_b32_e32 v237, 3, v236
	v_lshlrev_b32_e32 v236, 4, v236
	v_mov_b32_e32 v238, 0x358637bd
	s_sub_u32 s36, s36, 0x118
	s_subb_u32 s37, s37, 0
	s_load_dwordx2 s[10:11], s[36:37], 0x70
	s_load_dwordx2 s[12:13], s[36:37], 0x58
	s_add_u32 s22, s20, 0x2f90000
	s_addc_u32 s23, s21, 0
	s_mov_b32 s8, -1
	s_waitcnt lgkmcnt(0)
	s_add_u32 s12, s12, 0x1000
	s_addc_u32 s13, s13, 0
	s_lshl_b32 s9, s6, 12
	s_add_u32 s24, s14, s9
	s_addc_u32 s25, s15, 0
	s_lshl_b32 s9, s6, 11
	s_add_u32 s9, s9, 0x9278100
	s_add_u32 s26, s20, s9
	s_addc_u32 s27, s21, 0
	global_load_dwordx2 v[204:205], v237, s[26:27] offset:0
	global_load_dwordx2 v[206:207], v237, s[26:27] offset:512
	global_load_dwordx2 v[208:209], v237, s[26:27] offset:1024
	global_load_dwordx2 v[210:211], v237, s[26:27] offset:1536
	global_load_dwordx4 v[188:191], v236, s[24:25] offset:0
	global_load_dwordx4 v[192:195], v236, s[24:25] offset:1024
	global_load_dwordx4 v[196:199], v236, s[24:25] offset:2048
	global_load_dwordx4 v[200:203], v236, s[24:25] offset:3072

.LBB0_1374:
	s_or_b64 exec, exec, s[0:1]
	v_readlane_b32 s12, v242, 1
	v_mov_b32_e32 v1, v137
	s_waitcnt lgkmcnt(0)
	v_readfirstlane_b32 s99, v137
	s_cmp_lg_u32 s99, 64
	s_cbranch_scc1 .Lxbi10_skip
	buffer_inv sc1
	s_waitcnt vmcnt(0)
.Lxbi10_skip:
	s_barrier
	s_ashr_i32 s2, s66, 3
	v_readlane_b32 s14, v242, 3
	v_readlane_b32 s15, v242, 4
	v_and_b32_e32 v0, 63, v1
	v_ashrrev_i32_e32 v2, 6, v1
	v_bfe_u32 v4, v1, 3, 3
	s_add_u32 s6, s14, 0x500000
	v_and_b32_e32 v5, 1, v2
	v_bfe_u32 v8, v1, 4, 2
	v_readlane_b32 s0, v242, 0
	v_lshl_or_b32 v93, v2, 5, v4
	v_lshrrev_b32_e32 v4, 1, v1
	v_lshlrev_b32_e32 v2, 12, v2
	v_lshlrev_b32_e32 v7, 4, v0
	s_addc_u32 s7, s15, 0
	v_bfe_u32 v6, v1, 1, 3
	s_and_b32 s1, s0, 7
	v_add3_u32 v114, 0, v2, v7
	v_bitop3_b32 v2, v8, v4, 7 bitop3:0x78
	s_mul_i32 s40, s1, s2
	s_ashr_i32 s0, s0, 3
	v_lshlrev_b32_e32 v115, 4, v2
	v_bitop3_b32 v2, v8, v6, 4 bitop3:0x36
	v_mov_b32_e32 v95, 0
	v_lshlrev_b32_e32 v94, 3, v8
	v_readlane_b32 s13, v242, 2
	v_and_b32_e32 v92, 15, v1
	s_add_i32 s40, s40, s0
	v_lshlrev_b32_e32 v116, 4, v2
	v_and_b32_e32 v2, 7, v1
	v_lshrrev_b32_e32 v4, 4, v1
	v_lshl_add_u64 v[96:97], s[94:95], 0, v[94:95]
	v_lshlrev_b32_e32 v94, 8, v5
	v_ashrrev_i32_e32 v3, 7, v1
	s_lshl_b32 s0, s40, 6
	v_bitop3_b32 v9, v8, v1, 7 bitop3:0x78
	v_bitop3_b32 v10, v8, v2, 4 bitop3:0x36
	v_xor_b32_e32 v2, v8, v1
	v_bitop3_b32 v1, v4, v1, 4 bitop3:0x36
	v_lshl_add_u64 v[6:7], s[12:13], 0, v[94:95]
	v_lshlrev_b32_e32 v94, 2, v92
	s_lshl_b32 s77, s40, 5
	s_and_b32 s51, s0, 64
	v_lshlrev_b32_e32 v1, 3, v1
	v_lshl_add_u64 v[98:99], v[6:7], 0, v[94:95]
	v_lshlrev_b32_e32 v94, 1, v92
	s_ashr_i32 s41, s40, 2
	s_and_b32 s50, s77, 64
	v_lshlrev_b32_e32 v117, 6, v3
	v_lshlrev_b32_e32 v2, 3, v2
	v_and_b32_e32 v4, 56, v1
	v_lshlrev_b32_e32 v120, 13, v3
	v_lshlrev_b32_e32 v122, 13, v5
	v_add_u32_e32 v1, 0, v115
	v_add_u32_e32 v3, 0, v116
	s_lshl_b32 s0, s51, 2
	v_lshl_add_u64 v[100:101], s[88:89], 0, v[94:95]
	v_lshlrev_b32_e32 v94, 4, v9
	v_or_b32_e32 v0, 48, v0
	v_and_b32_e32 v2, 56, v2
	v_lshlrev_b32_e32 v121, 7, v92
	v_add_u32_e32 v11, v1, v120
	v_add_u32_e32 v1, v1, v122
	v_add_u32_e32 v12, v3, v120
	v_add_u32_e32 v3, v3, v122
	s_add_u32 s76, s12, s0
	v_lshl_add_u64 v[102:103], s[14:15], 0, v[94:95]
	v_lshlrev_b32_e32 v94, 4, v10
	s_mov_b32 s9, 0
	v_lshlrev_b32_e32 v118, 6, v5
	v_lshlrev_b32_e32 v119, 2, v8
	s_addc_u32 s83, s13, 0
	v_lshl_or_b32 v123, v8, 7, v92
	s_lshl_b32 s72, s66, 5
	s_lshl_b32 s78, s40, 7
	s_lshl_b32 s73, s66, 7
	v_lshl_add_u64 v[104:105], s[14:15], 0, v[94:95]
	s_movk_i32 s67, 0x2000
	s_mov_b64 s[10:11], 0x4000
	s_mov_b64 s[46:47], 0x80
	s_mov_b64 s[16:17], 0x4080
	s_mov_b64 s[18:19], 0x100
	s_mov_b64 s[20:21], 0x4100
	s_mov_b64 s[22:23], 0x180
	s_mov_b64 s[24:25], 0x4180
	s_mov_b64 s[26:27], 0x200
	v_mov_b32_e32 v124, 0x358637bd
	s_movk_i32 s79, 0x700
	s_movk_i32 s84, 0x1600
	s_mov_b32 s85, 0x5b76000
	v_lshlrev_b32_e32 v106, 1, v2
	v_lshlrev_b32_e32 v108, 1, v4
	v_add_u32_e32 v125, v11, v121
	v_add_u32_e32 v126, v1, v121
	v_add_u32_e32 v127, v12, v121
	v_add_u32_e32 v128, v3, v121
	v_lshlrev_b32_e32 v110, 2, v0
	v_mov_b32_e32 v129, 0xc0
	v_mov_b32_e32 v130, 0x3800000
	v_mov_b32_e32 v131, 0x2800000
	v_bfrev_b32_e32 v132, 32
	v_mov_b32_e32 v133, 0x3000000
	s_mov_b32 s82, 0
	s_mov_b64 s[80:81], 0x600
	s_mov_b64 s[86:87], 0x4600
	s_mov_b64 s[88:89], 0x680
	s_mov_b64 s[90:91], 0x4680
	s_mov_b64 s[28:29], 0x4780
	s_mov_b64 s[30:31], 0x8000
	s_mov_b64 s[34:35], 0xc000
	v_writelane_b32 v242, s2, 54
	s_branch .LBB0_1378

.LBB0_1831:
	s_or_b64 exec, exec, s[0:1]
	s_waitcnt lgkmcnt(0)
	v_mov_b32_e32 v0, v137
	v_readlane_b32 s12, v242, 0
	v_readfirstlane_b32 s99, v137
	s_cmp_lg_u32 s99, 64
	s_cbranch_scc1 .Lxbi11_skip
	buffer_inv sc1
	s_waitcnt vmcnt(0)
.Lxbi11_skip:
	s_barrier
	s_cmpk_gt_i32 s12, 0x1df
	s_cbranch_scc1 .LBB0_1851
	v_readlane_b32 s0, v241, 45
	v_readlane_b32 s1, v241, 46
	v_lshlrev_b32_e32 v9, 4, v0
	s_movk_i32 s0, 0x70
	v_bitop3_b32 v11, v9, s0, v0 bitop3:0x48
	v_readlane_b32 s0, v242, 46
	v_mov_b32_e32 v45, 0
	v_and_b32_e32 v44, 0xf0, v9
	v_readlane_b32 s1, v242, 47
	v_bfe_u32 v8, v0, 4, 2
	v_and_b32_e32 v10, 0xffffff80, v9
	v_lshl_add_u64 v[46:47], s[0:1], 0, v[44:45]
	v_readlane_b32 s0, v241, 47
	v_lshlrev_b32_e32 v44, 4, v8
	v_readlane_b32 s1, v241, 48
	v_ashrrev_i32_e32 v9, 1, v0
	v_and_b32_e32 v133, 0xffffffe0, v9
	v_lshl_add_u64 v[48:49], s[0:1], 0, v[44:45]
	s_lshl_b32 s0, s12, 12
	v_add_u32_e32 v16, 0x100, v0
	v_add_u32_e32 v19, 0x200, v0
	v_add_u32_e32 v22, 0x300, v0
	s_add_i32 s13, s0, 0x12000
	v_lshrrev_b32_e32 v9, 5, v9
	s_movk_i32 s0, 0x3000
	v_lshlrev_b32_e32 v4, 3, v0
	v_ashrrev_i32_e32 v13, 4, v0
	v_ashrrev_i32_e32 v16, 4, v16
	v_ashrrev_i32_e32 v19, 4, v19
	v_ashrrev_i32_e32 v22, 4, v22
	v_mul_lo_u32 v29, v9, s0
	s_movk_i32 s0, 0x600
	v_and_b32_e32 v132, 15, v0
	v_bfe_u32 v1, v0, 1, 3
	v_lshrrev_b32_e32 v5, 4, v0
	v_and_b32_e32 v2, 0xffffffc0, v4
	v_xor_b32_e32 v15, v13, v0
	v_xor_b32_e32 v18, v16, v0
	v_xor_b32_e32 v21, v19, v0
	v_xor_b32_e32 v0, v22, v0
	v_mad_u32_u24 v135, v8, s0, v29
	s_mov_b32 s0, 0xb000
	v_add_u32_e32 v6, 0x800, v2
	v_lshl_add_u32 v12, v132, 8, 0
	v_lshlrev_b32_e32 v15, 4, v15
	v_lshlrev_b32_e32 v18, 4, v18
	v_lshlrev_b32_e32 v21, 4, v21
	v_lshlrev_b32_e32 v0, 4, v0
	v_bitop3_b32 v24, v5, v1, 3 bitop3:0x6c
	v_lshlrev_b32_e32 v25, 7, v132
	v_bitop3_b32 v1, v8, v1, 4 bitop3:0x36
	v_bitop3_b32 v5, v5, v132, 3 bitop3:0x6c
	v_bitop3_b32 v26, v8, v132, 4 bitop3:0x36
	v_bitop3_b32 v27, v8, v132, 8 bitop3:0x36
	v_bitop3_b32 v28, v8, v132, 12 bitop3:0x36
	v_mul_lo_u32 v29, v9, s0
	s_movk_i32 s0, 0x1600
	v_ashrrev_i32_e32 v3, 31, v2
	v_and_b32_e32 v4, 56, v4
	v_ashrrev_i32_e32 v7, 31, v6
	v_add_u32_e32 v10, 0, v10
	v_lshl_add_u32 v14, v13, 8, 0
	v_and_b32_e32 v15, 0xf0, v15
	v_lshl_add_u32 v17, v16, 8, 0
	v_and_b32_e32 v18, 0xf0, v18
	v_lshl_add_u32 v20, v19, 8, 0
	v_and_b32_e32 v21, 0xf0, v21
	v_lshl_add_u32 v23, v22, 8, 0
	v_and_b32_e32 v0, 0xf0, v0
	v_lshlrev_b32_e32 v24, 4, v24
	v_sub_u32_e32 v25, v12, v25
	v_lshlrev_b32_e32 v1, 4, v1
	v_lshlrev_b32_e32 v5, 4, v5
	v_lshlrev_b32_e32 v26, 4, v26
	v_lshlrev_b32_e32 v27, 4, v27
	v_lshlrev_b32_e32 v28, 4, v28
	v_mad_u32_u24 v138, v8, s0, v29
	s_lshl_b32 s0, s12, 13
	v_lshlrev_b32_e32 v8, 5, v8
	s_mov_b64 s[24:25], s[42:43]
	s_mov_b32 s3, 0
	v_cmp_eq_u32_e32 vcc, 0, v132
	s_lshl_b32 s14, s66, 12
	v_lshl_or_b32 v134, s12, 6, v132
	s_lshl_b32 s15, s66, 6
	v_lshlrev_b32_e32 v139, 7, v22
	s_add_i32 s16, s0, 0xc000
	s_lshl_b32 s17, s66, 13
	v_lshlrev_b32_e32 v140, 7, v19
	v_lshlrev_b32_e32 v141, 7, v16
	v_lshlrev_b32_e32 v142, 7, v13
	v_lshl_or_b32 v143, v9, 8, v8
	v_lshlrev_b64 v[50:51], 1, v[2:3]
	v_lshlrev_b32_e32 v52, 1, v4
	v_mov_b32_e32 v53, v45
	v_lshlrev_b64 v[54:55], 1, v[6:7]
	v_add_u32_e32 v144, v10, v11
	v_add_u32_e32 v145, v14, v15
	v_add_u32_e32 v146, v17, v18
	v_add_u32_e32 v147, v20, v21
	v_add_u32_e32 v148, v23, v0
	s_mov_b64 s[4:5], 0x1200
	s_movk_i32 s18, 0x1000
	s_mov_b64 s[6:7], 0x1240
	s_mov_b64 s[8:9], 0x1280
	s_mov_b64 s[10:11], 0x12c0
	v_add_u32_e32 v149, v25, v24
	v_add_u32_e32 v150, v25, v1
	v_add_u32_e32 v151, v12, v5
	v_add_u32_e32 v152, v12, v26
	v_add_u32_e32 v153, v12, v27
	v_add_u32_e32 v154, v12, v28
	v_mov_b32_e32 v155, 0x1000
	s_branch .LBB0_1834

.LBB0_1903:
	s_or_b64 exec, exec, s[0:1]
	v_readlane_b32 s0, v242, 1
	v_readlane_b32 s2, v242, 3
	v_readlane_b32 s3, v242, 4
	s_add_u32 s48, s2, 0x30f4040
	v_mbcnt_hi_u32_b32 v136, -1, v136
	s_addc_u32 s49, s3, 0
	s_add_i32 s33, 0, 0x12000
	s_waitcnt lgkmcnt(0)
	v_and_b32_e32 v0, 64, v136
	v_mov_b32_e32 v143, -1
	s_mov_b32 s59, 0
	v_mov_b32_e32 v89, 0
	v_mov_b32_e32 v138, s33
	s_mov_b32 s40, 0x1c000
	s_movk_i32 s41, 0xfefe
	s_movk_i32 s50, 0x180
	s_movk_i32 s51, 0x580
	s_movk_i32 s45, 0x600
	v_xor_b32_e32 v139, 16, v136
	v_add_u32_e32 v140, 64, v0
	v_xor_b32_e32 v141, 32, v136
	v_mov_b32_e32 v142, 0xf149f2ca
	v_readfirstlane_b32 s99, v137
	s_cmp_lg_u32 s99, 64
	s_cbranch_scc1 .Lxbi12_skip
	buffer_inv sc1
	s_waitcnt vmcnt(0)
.Lxbi12_skip:
	s_barrier
	v_readlane_b32 s1, v242, 2
	s_branch .LBB0_1907

.Lxbi13_skip:
	s_barrier
	s_nop 0
	v_ashrrev_i32_e32 v1, 6, v0
	s_waitcnt vmcnt(7)
	v_lshl_add_u32 v4, s0, 2, v1
	s_movk_i32 s0, 0x2800
	v_cmp_gt_i32_e32 vcc, s0, v4
	s_and_saveexec_b64 s[0:1], vcc
	s_cbranch_execz .LBB0_2031
	s_waitcnt vmcnt(0) lgkmcnt(0)
	v_readfirstlane_b32 s2, v4
	v_readlane_b32 s4, v242, 42
	v_readlane_b32 s5, v242, 43
	v_readlane_b32 s6, v242, 3
	v_readlane_b32 s7, v242, 4
	s_load_dword s3, s[4:5], 0x0
	s_sub_u32 s20, s4, 0x118
	s_subb_u32 s21, s5, 0
	s_load_dwordx2 s[22:23], s[20:21], 0xe0
	s_load_dwordx2 s[24:25], s[20:21], 0xe8
	v_and_b32_e32 v11, 63, v137
	v_lshrrev_b32_e32 v9, 4, v11
	v_and_b32_e32 v11, 15, v11
	v_lshlrev_b32_e32 v11, 2, v11
	v_lshl_add_u32 v5, v9, 6, v11
	v_and_b32_e32 v10, 1, v9
	v_add_u32_e32 v10, 4, v10
	v_lshl_add_u32 v7, v10, 6, v11
	v_lshlrev_b32_e32 v6, 2, v5
	v_lshlrev_b32_e32 v8, 2, v7
	v_lshlrev_b32_e32 v5, 1, v5
	v_lshlrev_b32_e32 v7, 1, v7
	v_lshlrev_b32_e32 v9, 2, v9
	v_lshlrev_b32_e32 v10, 2, v10
	v_mov_b32_e32 v126, 0x3a27c5ac
	v_mov_b32_e32 v127, 0x3c800000
	s_add_u32 s8, s6, 0xddc8100
	s_addc_u32 s9, s7, 0
	s_add_u32 s10, s6, 0xe548100
	s_addc_u32 s11, s7, 0
	s_add_u32 s12, s6, 0xd5f8100
	s_addc_u32 s13, s7, 0
	s_add_u32 s14, s6, 0x5b78d00
	s_addc_u32 s15, s7, 0
	s_add_u32 s16, s6, 0xdd78100
	s_addc_u32 s17, s7, 0
	s_add_u32 s18, s6, 0x30f8600
	s_addc_u32 s19, s7, 0
	s_waitcnt lgkmcnt(0)
	s_lshl_b32 s3, s3, 2
	s_add_u32 s22, s22, 0x600
	s_addc_u32 s23, s23, 0
	s_add_u32 s24, s24, 0x600
	s_addc_u32 s25, s25, 0
	global_load_dwordx4 v[12:15], v6, s[22:23]
	global_load_dwordx4 v[16:19], v8, s[22:23]
	global_load_dwordx4 v[20:23], v6, s[24:25]
	global_load_dwordx4 v[24:27], v8, s[24:25]
	s_mul_i32 s4, s2, 0x300
	s_add_u32 s20, s8, s4
	s_addc_u32 s21, s9, 0
	s_add_u32 s22, s10, s4
	s_addc_u32 s23, s11, 0
	s_add_u32 s24, s12, s4
	s_addc_u32 s25, s13, 0
	s_mul_i32 s4, s2, 0x1600
	s_add_u32 s26, s14, s4
	s_addc_u32 s27, s15, 0
	s_lshl_b32 s4, s2, 5
	s_add_u32 s28, s16, s4
	s_addc_u32 s29, s17, 0
	global_load_dwordx2 v[28:29], v5, s[20:21]
	global_load_dwordx2 v[30:31], v5, s[22:23]
	global_load_dwordx2 v[32:33], v5, s[24:25]
	global_load_dwordx4 v[34:37], v6, s[26:27]
	global_load_dword v38, v9, s[28:29]
	global_load_dwordx2 v[40:41], v7, s[20:21]
	global_load_dwordx2 v[42:43], v7, s[22:23]
	global_load_dwordx2 v[44:45], v7, s[24:25]
	global_load_dwordx4 v[46:49], v8, s[26:27]
	global_load_dword v50, v10, s[28:29]
	s_waitcnt vmcnt(0)

.Lxbi14_skip:
	s_barrier
	v_readlane_b32 s0, v242, 0
	v_and_b32_e32 v0, 63, v3
	s_waitcnt vmcnt(3)
	v_ashrrev_i32_e32 v10, 6, v3
	v_bfe_u32 v18, v3, 4, 2
	v_lshrrev_b32_e32 v2, 1, v3
	v_bfe_u32 v4, v3, 1, 3
	v_lshlrev_b32_e32 v136, 4, v0
	v_bitop3_b32 v0, v18, v2, 7 bitop3:0x78
	v_add_u32_e32 v6, 4, v10
	v_bfe_u32 v134, v3, 3, 3
	v_lshlrev_b32_e32 v140, 4, v0
	v_bitop3_b32 v0, v18, v4, 4 bitop3:0x36
	v_lshlrev_b32_e32 v4, 3, v6
	v_or_b32_e32 v5, v4, v134
	s_waitcnt vmcnt(2)
	v_lshrrev_b32_e32 v20, 1, v5
	v_ashrrev_i32_e32 v5, 31, v4
	v_lshlrev_b64 v[86:87], 10, v[4:5]
	v_add_u32_e32 v5, 8, v10
	s_and_b32 s1, s0, 7
	v_xor_b32_e32 v7, v20, v3
	v_lshlrev_b32_e32 v144, 10, v6
	v_lshlrev_b32_e32 v6, 3, v5
	s_mul_i32 s18, s1, s57
	s_ashr_i32 s0, s0, 3
	v_lshlrev_b32_e32 v4, 3, v7
	v_or_b32_e32 v7, v6, v134
	v_ashrrev_i32_e32 v1, 7, v3
	v_and_b32_e32 v13, 1, v10
	s_add_i32 s18, s18, s0
	s_movk_i32 s0, 0x50
	v_lshrrev_b32_e32 v21, 1, v7
	v_and_b32_e32 v15, 15, v3
	v_lshlrev_b32_e32 v141, 4, v0
	v_mul_lo_u32 v0, v1, s0
	v_lshlrev_b32_e32 v80, 7, v13
	v_mov_b32_e32 v81, 0
	v_xor_b32_e32 v8, v21, v3
	v_ashrrev_i32_e32 v7, 31, v6
	v_lshlrev_b32_e32 v145, 10, v5
	v_add_u32_e32 v5, 12, v10
	v_or_b32_e32 v16, v0, v15
	v_lshl_or_b32 v142, v18, 2, v0
	v_lshl_add_u64 v[0:1], s[54:55], 0, v[80:81]
	v_lshlrev_b32_e32 v80, 1, v15
	v_lshlrev_b64 v[88:89], 10, v[6:7]
	v_lshlrev_b32_e32 v6, 3, v8
	v_lshlrev_b32_e32 v8, 3, v5
	v_lshlrev_b32_e32 v146, 10, v5
	v_add_u32_e32 v5, 16, v10
	v_lshl_or_b32 v135, v10, 5, v134
	v_lshlrev_b32_e32 v139, 12, v10
	v_lshl_add_u64 v[82:83], v[0:1], 0, v[80:81]
	v_lshlrev_b32_e32 v0, 3, v10
	v_lshlrev_b32_e32 v143, 10, v10
	v_or_b32_e32 v7, v8, v134
	v_ashrrev_i32_e32 v9, 31, v8
	v_lshlrev_b32_e32 v10, 3, v5
	v_lshrrev_b32_e32 v7, 1, v7
	v_lshlrev_b64 v[90:91], 10, v[8:9]
	v_or_b32_e32 v9, v10, v134
	v_xor_b32_e32 v11, v7, v3
	v_lshrrev_b32_e32 v9, 1, v9
	v_lshlrev_b32_e32 v147, 10, v5
	v_xor_b32_e32 v5, v18, v3
	v_lshlrev_b32_e32 v8, 3, v11
	v_xor_b32_e32 v12, v9, v3
	v_ashrrev_i32_e32 v11, 31, v10
	v_lshlrev_b32_e32 v5, 3, v5
	v_lshlrev_b64 v[92:93], 10, v[10:11]
	v_lshlrev_b32_e32 v10, 3, v12
	v_and_b32_e32 v12, 56, v5
	v_lshrrev_b32_e32 v5, 4, v3
	v_or_b32_e32 v1, v0, v134
	v_or_b32_e32 v11, 4, v5
	v_bitop3_b32 v5, v5, v3, 4 bitop3:0x36
	v_lshrrev_b32_e32 v17, 1, v1
	v_ashrrev_i32_e32 v1, 31, v0
	v_lshlrev_b32_e32 v5, 3, v5
	v_lshlrev_b64 v[84:85], 10, v[0:1]
	v_and_b32_e32 v14, 56, v5
	v_lshlrev_b64 v[0:1], 11, v[0:1]
	v_bitop3_b32 v5, v17, 7, v3 bitop3:0x48
	v_readlane_b32 s0, v242, 1
	v_xor_b32_e32 v2, v17, v3
	v_lshlrev_b32_e32 v148, 7, v16
	v_lshl_or_b32 v16, v5, 4, v0
	v_mov_b32_e32 v17, v1
	v_readlane_b32 s1, v242, 2
	v_readlane_b32 s2, v242, 3
	v_readlane_b32 s3, v242, 4
	s_mov_b64 s[0:1], 0x30f8180
	v_bitop3_b32 v5, v20, 7, v3 bitop3:0x48
	v_lshl_add_u64 v[16:17], s[2:3], 0, v[16:17]
	v_lshl_add_u64 v[94:95], v[16:17], 0, s[0:1]
	v_lshl_or_b32 v16, v5, 4, v0
	v_mov_b32_e32 v17, v1
	v_lshl_add_u64 v[16:17], s[2:3], 0, v[16:17]
	s_mov_b64 s[0:1], 0x3108180
	v_bitop3_b32 v5, v21, 7, v3 bitop3:0x48
	v_lshl_add_u64 v[96:97], v[16:17], 0, s[0:1]
	v_lshl_or_b32 v16, v5, 4, v0
	v_mov_b32_e32 v17, v1
	v_lshl_add_u64 v[16:17], s[2:3], 0, v[16:17]
	s_mov_b64 s[0:1], 0x3118180
	v_bitop3_b32 v5, v7, 7, v3 bitop3:0x48
	v_lshl_add_u64 v[98:99], v[16:17], 0, s[0:1]
	v_lshl_or_b32 v16, v5, 4, v0
	v_mov_b32_e32 v17, v1
	v_bitop3_b32 v5, v9, 7, v3 bitop3:0x48
	v_lshl_add_u64 v[16:17], s[2:3], 0, v[16:17]
	s_mov_b64 s[0:1], 0x3128180
	v_lshl_or_b32 v0, v5, 4, v0
	v_lshl_add_u64 v[100:101], v[16:17], 0, s[0:1]
	v_lshl_add_u64 v[0:1], s[2:3], 0, v[0:1]
	s_mov_b64 s[0:1], 0x3138180
	v_lshl_add_u64 v[102:103], v[0:1], 0, s[0:1]
	v_bitop3_b32 v0, v18, 7, v3 bitop3:0x48
	v_lshlrev_b32_e32 v2, 3, v2
	v_lshlrev_b32_e32 v80, 4, v0
	v_bitop3_b32 v0, v11, 7, v3 bitop3:0x48
	v_add_u32_e32 v19, 0, v139
	v_and_b32_e32 v2, 56, v2
	v_and_b32_e32 v4, 56, v4
	v_and_b32_e32 v6, 56, v6
	v_and_b32_e32 v8, 56, v8
	v_and_b32_e32 v10, 56, v10
	v_lshl_add_u64 v[104:105], s[2:3], 0, v[80:81]
	v_lshlrev_b32_e32 v80, 4, v0
	s_mov_b32 s19, 0
	v_add_u32_e32 v138, 0, v136
	v_lshlrev_b32_e32 v149, 13, v13
	v_lshlrev_b32_e32 v150, 7, v15
	v_lshl_add_u64 v[106:107], s[2:3], 0, v[80:81]
	v_lshlrev_b32_e32 v80, 1, v2
	v_lshlrev_b32_e32 v108, 1, v4
	v_lshlrev_b32_e32 v110, 1, v6
	v_lshlrev_b32_e32 v112, 1, v8
	v_lshlrev_b32_e32 v114, 1, v10
	v_lshlrev_b32_e32 v116, 1, v12
	v_add_u32_e32 v151, v19, v136
	v_lshlrev_b32_e32 v118, 1, v14
	s_mov_b64 s[0:1], 0x4000
	s_mov_b64 s[2:3], 0x8000
	s_mov_b64 s[4:5], 0xc000
	s_mov_b64 s[6:7], 0xc00080
	s_mov_b64 s[8:9], 0xc04080
	s_mov_b64 s[10:11], 0xc08080
	s_mov_b64 s[12:13], 0xc0c080
	s_waitcnt vmcnt(0)
	s_branch .LBB0_2085

.LBB0_2141:
	s_or_b64 exec, exec, s[0:1]
	s_waitcnt lgkmcnt(0)
	v_mov_b32_e32 v0, v137
	v_readfirstlane_b32 s99, v137
	s_cmp_lg_u32 s99, 64
	s_cbranch_scc1 .Lxbi15_skip
	buffer_inv sc1
	s_waitcnt vmcnt(0)
.Lxbi15_skip:
	s_barrier
	v_readlane_b32 s0, v242, 0
	v_ashrrev_i32_e32 v1, 6, v0
	s_nop 0
	v_lshl_add_u32 v1, s0, 2, v1
	v_mul_lo_u32 v16, v1, s56
	v_add_u32_e32 v1, s56, v16
	v_min_i32_e32 v62, 0x2800, v1
	v_cmp_lt_i32_e32 vcc, v16, v62
	s_and_saveexec_b64 s[0:1], vcc
	s_xor_b64 s[0:1], exec, s[0:1]
	s_cbranch_execz .LBB0_2147
	v_readfirstlane_b32 s6, v16
	v_readfirstlane_b32 s7, v62
	v_readlane_b32 s36, v242, 42
	v_readlane_b32 s37, v242, 43
	v_readlane_b32 s14, v242, 1
	v_readlane_b32 s15, v242, 2
	v_readlane_b32 s20, v242, 3
	v_readlane_b32 s21, v242, 4
	v_and_b32_e32 v236, 63, v137
	v_lshlrev_b32_e32 v237, 3, v236
	v_lshlrev_b32_e32 v236, 4, v236
	v_mov_b32_e32 v238, 0x358637bd
	s_sub_u32 s36, s36, 0x118
	s_subb_u32 s37, s37, 0
	s_load_dwordx2 s[10:11], s[36:37], 0x60
	s_load_dwordx2 s[12:13], s[36:37], 0x68
	s_add_u32 s22, s20, 0x2f90000
	s_addc_u32 s23, s21, 0
	s_mov_b32 s8, -1
	s_waitcnt lgkmcnt(0)
	s_add_u32 s10, s10, 0x1000
	s_addc_u32 s11, s11, 0
	s_add_u32 s12, s12, 0x1000
	s_addc_u32 s13, s13, 0
	s_lshl_b32 s9, s6, 12
	s_add_u32 s24, s14, s9
	s_addc_u32 s25, s15, 0
	s_lshl_b32 s9, s6, 11
	s_add_u32 s9, s9, 0x9278100
	s_add_u32 s26, s20, s9
	s_addc_u32 s27, s21, 0
	global_load_dwordx2 v[204:205], v237, s[26:27] offset:0
	global_load_dwordx2 v[206:207], v237, s[26:27] offset:512
	global_load_dwordx2 v[208:209], v237, s[26:27] offset:1024
	global_load_dwordx2 v[210:211], v237, s[26:27] offset:1536
	global_load_dwordx4 v[188:191], v236, s[24:25] offset:0
	global_load_dwordx4 v[192:195], v236, s[24:25] offset:1024
	global_load_dwordx4 v[196:199], v236, s[24:25] offset:2048
	global_load_dwordx4 v[200:203], v236, s[24:25] offset:3072

.Lxbi16_skip:
	s_barrier
	v_readlane_b32 s0, v242, 0
	v_and_b32_e32 v0, 63, v1
	v_ashrrev_i32_e32 v2, 6, v1
	v_bfe_u32 v7, v1, 3, 3
	v_and_b32_e32 v4, 1, v2
	v_bfe_u32 v6, v1, 4, 2
	v_lshl_or_b32 v82, v2, 5, v7
	v_lshrrev_b32_e32 v7, 1, v1
	v_lshlrev_b32_e32 v2, 12, v2
	v_lshlrev_b32_e32 v0, 4, v0
	v_bfe_u32 v8, v1, 1, 3
	v_add3_u32 v83, 0, v2, v0
	v_bitop3_b32 v0, v6, v7, 7 bitop3:0x78
	v_lshlrev_b32_e32 v84, 4, v0
	v_bitop3_b32 v0, v6, v8, 4 bitop3:0x36
	v_lshlrev_b32_e32 v85, 4, v0
	v_and_b32_e32 v0, 7, v1
	v_bitop3_b32 v8, v6, v0, 4 bitop3:0x36
	v_lshrrev_b32_e32 v0, 2, v1
	v_ashrrev_i32_e32 v3, 7, v1
	s_and_b32 s1, s0, 7
	v_lshrrev_b32_e32 v2, 4, v1
	v_and_b32_e32 v0, 12, v0
	v_and_b32_e32 v5, 15, v1
	s_mul_i32 s24, s1, s57
	s_ashr_i32 s0, s0, 3
	v_bitop3_b32 v7, v6, v1, 7 bitop3:0x78
	v_lshl_or_b32 v87, v3, 6, v0
	v_xor_b32_e32 v0, v6, v1
	v_bitop3_b32 v1, v2, v1, 4 bitop3:0x36
	s_add_i32 s24, s24, s0
	v_mov_b32_e32 v65, 0
	v_lshlrev_b32_e32 v1, 3, v1
	v_lshlrev_b32_e32 v64, 1, v5
	v_readlane_b32 s0, v242, 1
	v_lshlrev_b32_e32 v0, 3, v0
	v_and_b32_e32 v2, 56, v1
	v_lshlrev_b32_e32 v88, 13, v3
	v_lshlrev_b32_e32 v90, 13, v4
	v_add_u32_e32 v1, 0, v84
	v_add_u32_e32 v3, 0, v85
	v_lshl_add_u64 v[66:67], s[52:53], 0, v[64:65]
	v_lshlrev_b32_e32 v64, 4, v7
	v_readlane_b32 s2, v242, 3
	v_readlane_b32 s3, v242, 4
	v_lshlrev_b32_e32 v86, 6, v4
	v_and_b32_e32 v0, 56, v0
	v_lshlrev_b32_e32 v89, 7, v5
	v_add_u32_e32 v4, v1, v88
	v_add_u32_e32 v1, v1, v90
	v_add_u32_e32 v6, v3, v88
	v_add_u32_e32 v3, v3, v90
	v_readlane_b32 s1, v242, 2
	v_lshl_add_u64 v[68:69], s[2:3], 0, v[64:65]
	v_lshlrev_b32_e32 v64, 4, v8
	s_mov_b32 s25, 0
	s_lshl_b32 s26, s24, 5
	s_lshl_b32 s27, s24, 7
	v_lshl_add_u64 v[70:71], s[2:3], 0, v[64:65]
	v_lshlrev_b32_e32 v64, 1, v0
	v_add_u32_e32 v91, 0x4000, v83
	v_lshlrev_b32_e32 v72, 1, v2
	s_mov_b64 s[0:1], 0x4000
	v_add_u32_e32 v92, 0x400, v83
	v_add_u32_e32 v93, 0x4400, v83
	s_mov_b64 s[2:3], 0x8000
	v_add_u32_e32 v94, 0x800, v83
	v_add_u32_e32 v95, 0x4800, v83
	s_mov_b64 s[4:5], 0xc000
	v_add_u32_e32 v96, 0xc00, v83
	v_add_u32_e32 v97, 0x4c00, v83
	s_movk_i32 s28, 0x1600
	s_mov_b64 s[6:7], 0x30f8180
	s_mov_b64 s[8:9], 0x1900080
	s_mov_b64 s[10:11], 0x30fc180
	s_mov_b64 s[12:13], 0x1904080
	s_mov_b64 s[14:15], 0x3100180
	s_mov_b64 s[16:17], 0x1908080
	s_mov_b64 s[18:19], 0x3104180
	s_mov_b64 s[20:21], 0x190c080
	v_add_u32_e32 v98, v4, v89
	v_add_u32_e32 v99, v1, v89
	v_add_u32_e32 v100, v6, v89
	v_add_u32_e32 v101, v3, v89
	s_branch .LBB0_2201

.Lxbi17_skip:
	s_barrier
	v_readlane_b32 s0, v242, 0
	v_and_b32_e32 v0, 63, v3
	v_bfe_u32 v11, v3, 4, 2
	v_lshrrev_b32_e32 v2, 1, v3
	v_ashrrev_i32_e32 v5, 6, v3
	v_bfe_u32 v4, v3, 1, 3
	v_lshlrev_b32_e32 v136, 4, v0
	v_bitop3_b32 v0, v11, v2, 7 bitop3:0x78
	v_lshlrev_b32_e32 v140, 4, v0
	v_bitop3_b32 v0, v11, v4, 4 bitop3:0x36
	v_add_u32_e32 v4, 4, v5
	v_bfe_u32 v134, v3, 3, 3
	v_lshlrev_b32_e32 v2, 3, v4
	s_and_b32 s1, s0, 7
	v_or_b32_e32 v6, v2, v134
	s_mul_i32 s18, s1, s57
	s_ashr_i32 s0, s0, 3
	v_lshrrev_b32_e32 v18, 1, v6
	v_ashrrev_i32_e32 v1, 7, v3
	s_add_i32 s18, s18, s0
	s_movk_i32 s0, 0x50
	s_movk_i32 s2, 0xb00
	v_xor_b32_e32 v6, v18, v3
	v_lshlrev_b32_e32 v141, 4, v0
	v_mul_lo_u32 v0, v1, s0
	v_mad_i64_i32 v[86:87], s[0:1], v2, s2, 0
	v_lshlrev_b32_e32 v2, 3, v6
	v_add_u32_e32 v6, 8, v5
	v_lshlrev_b32_e32 v144, 10, v4
	v_lshlrev_b32_e32 v4, 3, v6
	v_and_b32_e32 v7, 1, v5
	v_or_b32_e32 v8, v4, v134
	v_and_b32_e32 v9, 15, v3
	v_lshlrev_b32_e32 v80, 7, v7
	v_mov_b32_e32 v81, 0
	v_lshrrev_b32_e32 v19, 1, v8
	v_or_b32_e32 v14, v0, v9
	v_lshl_or_b32 v142, v11, 2, v0
	v_lshl_add_u64 v[0:1], s[54:55], 0, v[80:81]
	v_lshlrev_b32_e32 v80, 1, v9
	v_xor_b32_e32 v8, v19, v3
	v_lshl_or_b32 v135, v5, 5, v134
	v_lshlrev_b32_e32 v139, 12, v5
	v_lshl_add_u64 v[82:83], v[0:1], 0, v[80:81]
	v_lshlrev_b32_e32 v1, 3, v5
	v_lshlrev_b32_e32 v143, 10, v5
	v_mad_i64_i32 v[88:89], s[0:1], v4, s2, 0
	v_lshlrev_b32_e32 v4, 3, v8
	v_add_u32_e32 v8, 12, v5
	v_add_u32_e32 v5, 16, v5
	v_or_b32_e32 v0, v1, v134
	v_lshlrev_b32_e32 v145, 10, v6
	v_lshlrev_b32_e32 v6, 3, v8
	v_lshlrev_b32_e32 v146, 10, v8
	v_lshlrev_b32_e32 v8, 3, v5
	s_movk_i32 s20, 0x1600
	v_lshrrev_b32_e32 v16, 1, v0
	v_mad_i64_i32 v[84:85], s[0:1], v1, s2, 0
	v_mad_i64_i32 v[90:91], s[0:1], v6, s2, 0
	v_mad_i64_i32 v[92:93], s[0:1], v8, s2, 0
	v_lshlrev_b32_e32 v148, 7, v14
	v_mad_i64_i32 v[14:15], s[0:1], v1, s20, 0
	v_bitop3_b32 v1, v16, 7, v3 bitop3:0x48
	v_readlane_b32 s0, v242, 1
	v_xor_b32_e32 v0, v16, v3
	v_or_b32_e32 v10, v6, v134
	v_lshl_or_b32 v16, v1, 4, v14
	v_mov_b32_e32 v17, v15
	v_readlane_b32 s1, v242, 2
	v_readlane_b32 s2, v242, 3
	v_readlane_b32 s3, v242, 4
	v_lshrrev_b32_e32 v20, 1, v10
	s_mov_b64 s[0:1], 0x5b78180
	v_lshl_add_u64 v[16:17], s[2:3], 0, v[16:17]
	v_bitop3_b32 v1, v18, 7, v3 bitop3:0x48
	v_xor_b32_e32 v10, v20, v3
	v_lshl_add_u64 v[94:95], v[16:17], 0, s[0:1]
	v_lshl_or_b32 v16, v1, 4, v14
	v_mov_b32_e32 v17, v15
	v_lshlrev_b32_e32 v6, 3, v10
	v_or_b32_e32 v10, v8, v134
	v_lshl_add_u64 v[16:17], s[2:3], 0, v[16:17]
	s_mov_b64 s[0:1], 0x5ba4180
	v_bitop3_b32 v1, v19, 7, v3 bitop3:0x48
	v_lshrrev_b32_e32 v21, 1, v10
	v_lshlrev_b32_e32 v147, 10, v5
	v_xor_b32_e32 v5, v11, v3
	v_lshl_add_u64 v[96:97], v[16:17], 0, s[0:1]
	v_lshl_or_b32 v16, v1, 4, v14
	v_mov_b32_e32 v17, v15
	v_xor_b32_e32 v10, v21, v3
	v_lshlrev_b32_e32 v5, 3, v5
	v_lshl_add_u64 v[16:17], s[2:3], 0, v[16:17]
	s_mov_b64 s[0:1], 0x5bd0180
	v_bitop3_b32 v1, v20, 7, v3 bitop3:0x48
	v_lshlrev_b32_e32 v8, 3, v10
	v_and_b32_e32 v10, 56, v5
	v_lshrrev_b32_e32 v5, 4, v3
	v_lshl_add_u64 v[98:99], v[16:17], 0, s[0:1]
	v_lshl_or_b32 v16, v1, 4, v14
	v_bitop3_b32 v1, v21, 7, v3 bitop3:0x48
	v_or_b32_e32 v22, 4, v5
	v_bitop3_b32 v5, v5, v3, 4 bitop3:0x36
	v_mov_b32_e32 v17, v15
	v_lshl_or_b32 v14, v1, 4, v14
	v_bitop3_b32 v1, v11, 7, v3 bitop3:0x48
	v_lshlrev_b32_e32 v0, 3, v0
	v_lshlrev_b32_e32 v5, 3, v5
	v_lshl_add_u64 v[16:17], s[2:3], 0, v[16:17]
	s_mov_b64 s[0:1], 0x5bfc180
	v_lshlrev_b32_e32 v80, 4, v1
	v_bitop3_b32 v1, v22, 7, v3 bitop3:0x48
	v_add_u32_e32 v13, 0, v139
	v_and_b32_e32 v0, 56, v0
	v_and_b32_e32 v2, 56, v2
	v_and_b32_e32 v4, 56, v4
	v_and_b32_e32 v6, 56, v6
	v_and_b32_e32 v8, 56, v8
	v_and_b32_e32 v12, 56, v5
	v_lshl_add_u64 v[100:101], v[16:17], 0, s[0:1]
	v_lshl_add_u64 v[14:15], s[2:3], 0, v[14:15]
	s_mov_b64 s[0:1], 0x5c28180
	v_lshl_add_u64 v[104:105], s[2:3], 0, v[80:81]
	v_lshlrev_b32_e32 v80, 4, v1
	s_mov_b32 s19, 0
	v_add_u32_e32 v138, 0, v136
	v_lshlrev_b32_e32 v149, 13, v7
	v_lshlrev_b32_e32 v150, 7, v9
	v_lshl_add_u64 v[102:103], v[14:15], 0, s[0:1]
	v_lshl_add_u64 v[106:107], s[2:3], 0, v[80:81]
	v_lshlrev_b32_e32 v80, 1, v0
	v_lshlrev_b32_e32 v108, 1, v2
	v_lshlrev_b32_e32 v110, 1, v4
	v_lshlrev_b32_e32 v112, 1, v6
	v_lshlrev_b32_e32 v114, 1, v8
	v_lshlrev_b32_e32 v116, 1, v10
	v_add_u32_e32 v151, v13, v136
	v_lshlrev_b32_e32 v118, 1, v12
	s_mov_b64 s[0:1], 0xb000
	s_mov_b64 s[2:3], 0x16000
	s_mov_b64 s[4:5], 0x21000
	s_mov_b64 s[6:7], 0x2980080
	s_mov_b64 s[8:9], 0x298b080
	s_mov_b64 s[10:11], 0x2996080
	s_mov_b64 s[12:13], 0x29a1080
	s_branch .LBB0_2259

.LBB0_2315:
	s_or_b64 exec, exec, s[0:1]
	s_waitcnt lgkmcnt(0)
	v_readfirstlane_b32 s99, v137
	s_cmp_lg_u32 s99, 64
	s_cbranch_scc1 .Lxbi18_skip
	buffer_inv sc1
	s_waitcnt vmcnt(0)
.Lxbi18_skip:
	s_barrier
	v_readlane_b32 s0, v242, 0
	v_ashrrev_i32_e32 v0, 6, v137
	s_nop 0
	v_lshl_add_u32 v0, s0, 2, v0
	v_mul_lo_u32 v0, v0, s56
	v_add_u32_e32 v1, s56, v0
	v_min_i32_e32 v26, 0x2800, v1
	v_cmp_lt_i32_e32 vcc, v0, v26
	s_and_saveexec_b64 s[0:1], vcc
	s_cbranch_execz .LBB0_2320
	v_readfirstlane_b32 s6, v0
	v_readfirstlane_b32 s7, v26
	v_readlane_b32 s36, v242, 42
	v_readlane_b32 s37, v242, 43
	v_readlane_b32 s14, v242, 1
	v_readlane_b32 s15, v242, 2
	v_readlane_b32 s20, v242, 3
	v_readlane_b32 s21, v242, 4
	v_and_b32_e32 v236, 63, v137
	v_lshlrev_b32_e32 v237, 3, v236
	v_lshlrev_b32_e32 v236, 4, v236
	v_mov_b32_e32 v238, 0x358637bd
	s_sub_u32 s36, s36, 0x118
	s_subb_u32 s37, s37, 0
	s_load_dwordx2 s[10:11], s[36:37], 0x70
	s_add_u32 s22, s20, 0x2f90000
	s_addc_u32 s23, s21, 0
	s_mov_b32 s8, -1
	s_waitcnt lgkmcnt(0)
	s_add_u32 s10, s10, 0x1000
	s_addc_u32 s11, s11, 0
	s_lshl_b32 s9, s6, 12
	s_add_u32 s24, s14, s9
	s_addc_u32 s25, s15, 0
	s_lshl_b32 s9, s6, 11
	s_add_u32 s9, s9, 0x9278100
	s_add_u32 s26, s20, s9
	s_addc_u32 s27, s21, 0
	global_load_dwordx2 v[204:205], v237, s[26:27] offset:0
	global_load_dwordx2 v[206:207], v237, s[26:27] offset:512
	global_load_dwordx2 v[208:209], v237, s[26:27] offset:1024
	global_load_dwordx2 v[210:211], v237, s[26:27] offset:1536
	global_load_dwordx4 v[188:191], v236, s[24:25] offset:0
	global_load_dwordx4 v[192:195], v236, s[24:25] offset:1024
	global_load_dwordx4 v[196:199], v236, s[24:25] offset:2048
	global_load_dwordx4 v[200:203], v236, s[24:25] offset:3072
